# combined: route 2-deep prefetch + pipelined route tail + hand-written one-hop XCD barrier (spin cap as in the original)
# speedup vs baseline: 1.0072x; 1.0072x over previous
.Lxb_poll_1:
	global_load_dword v8, v3, s[100:101] sc1
	s_waitcnt vmcnt(0)
	v_cmp_ne_u32_e32 vcc, v8, v6
	s_cbranch_vccnz .Lxb_acq_1
	s_sleep 1
	v_add_u32_e32 v16, 1, v16
	v_cmp_gt_u32_e32 vcc, 0x40000, v16
	s_cbranch_vccnz .Lxb_poll_1

.LBB0_1004:
	s_and_b32 s77, s76, 1
	s_mul_i32 s78, s77, 0x4800
	s_add_u32 s100, s58, 0x80
	s_addc_u32 s101, s59, 0
	v_lshl_add_u64 v[64:65], v[160:161], 0, s[100:101]
	v_lshl_add_u64 v[68:69], v[168:169], 0, s[100:101]
	v_lshl_add_u64 v[72:73], v[162:163], 0, s[100:101]
	v_lshl_add_u64 v[76:77], v[170:171], 0, s[100:101]
	v_lshl_add_u64 v[80:81], v[164:165], 0, s[100:101]
	v_lshl_add_u64 v[84:85], v[172:173], 0, s[100:101]
	v_lshl_add_u64 v[88:89], v[166:167], 0, s[100:101]
	v_lshl_add_u64 v[92:93], v[174:175], 0, s[100:101]
	v_add3_u32 v197, s78, v232, v231
	global_load_dwordx4 v[64:67], v[64:65], off
	s_nop 0
	global_load_dwordx4 v[68:71], v[68:69], off
	s_nop 0
	global_load_dwordx4 v[72:75], v[72:73], off
	s_nop 0
	global_load_dwordx4 v[76:79], v[76:77], off
	s_nop 0
	global_load_dwordx4 v[80:83], v[80:81], off
	s_nop 0
	global_load_dwordx4 v[84:87], v[84:85], off
	s_nop 0
	global_load_dwordx4 v[88:91], v[88:89], off
	s_nop 0
	global_load_dwordx4 v[92:95], v[92:93], off
	v_add3_u32 v198, s78, v234, v231
	ds_read_b128 v[242:245], v198 offset:36864
	ds_read_b128 v[238:241], v197
	ds_read_b128 v[246:249], v197 offset:4608
	ds_read_b128 v[200:203], v197 offset:9216
	ds_read_b128 v[204:207], v197 offset:13824
	s_waitcnt lgkmcnt(3)
	v_mfma_f32_32x32x16_bf16 v[48:63], v[238:241], v[242:245], v[48:63]
	ds_read_b128 v[208:211], v198 offset:36896
	ds_read_b128 v[238:241], v197 offset:32
	s_add_i32 s76, s76, 1
	s_xor_b32 s79, s77, 1
	s_xor_b32 s80, s77, 3
	s_mul_i32 s77, s79, 0x4800
	s_add_u32 s58, s58, 0x80
	s_mul_i32 s78, s80, 0x4800
	s_waitcnt lgkmcnt(4)
	v_mfma_f32_32x32x16_bf16 v[32:47], v[246:249], v[242:245], v[32:47]
	ds_read_b128 v[246:249], v197 offset:4640
	v_or_b32_e32 v250, s77, v128
	s_addc_u32 s59, s59, 0
	v_or_b32_e32 v251, s78, v128
	v_add_u32_e32 v252, v250, v233
	s_cmpk_lg_i32 s58, 0x780
	v_add_u32_e32 v177, v251, v233
	s_waitcnt lgkmcnt(4)
	v_mfma_f32_32x32x16_bf16 v[16:31], v[200:203], v[242:245], v[16:31]
	ds_read_b128 v[200:203], v197 offset:9248
	s_waitcnt lgkmcnt(4)
	v_mfma_f32_32x32x16_bf16 v[0:15], v[204:207], v[242:245], v[0:15]
	ds_read_b128 v[204:207], v197 offset:13856
	s_waitcnt lgkmcnt(3)
	v_mfma_f32_32x32x16_bf16 v[48:63], v[238:241], v[208:211], v[48:63]
	ds_read_b128 v[242:245], v198 offset:36928
	ds_read_b128 v[238:241], v197 offset:64
	s_waitcnt lgkmcnt(4)
	v_mfma_f32_32x32x16_bf16 v[32:47], v[246:249], v[208:211], v[32:47]
	ds_read_b128 v[246:249], v197 offset:4672
	s_waitcnt lgkmcnt(4)
	v_mfma_f32_32x32x16_bf16 v[16:31], v[200:203], v[208:211], v[16:31]
	ds_read_b128 v[200:203], v197 offset:9280
	s_waitcnt lgkmcnt(4)
	v_mfma_f32_32x32x16_bf16 v[0:15], v[204:207], v[208:211], v[0:15]
	ds_read_b128 v[204:207], v197 offset:13888
	s_waitcnt lgkmcnt(3)
	v_mfma_f32_32x32x16_bf16 v[48:63], v[238:241], v[242:245], v[48:63]
	ds_read_b128 v[208:211], v198 offset:36960
	ds_read_b128 v[238:241], v197 offset:96
	s_waitcnt lgkmcnt(4)
	v_mfma_f32_32x32x16_bf16 v[32:47], v[246:249], v[242:245], v[32:47]
	ds_read_b128 v[246:249], v197 offset:4704
	s_waitcnt lgkmcnt(4)
	v_mfma_f32_32x32x16_bf16 v[16:31], v[200:203], v[242:245], v[16:31]
	ds_read_b128 v[200:203], v197 offset:9312
	s_waitcnt lgkmcnt(4)
	v_mfma_f32_32x32x16_bf16 v[0:15], v[204:207], v[242:245], v[0:15]
	ds_read_b128 v[204:207], v197 offset:13920
	s_waitcnt lgkmcnt(3)
	v_mfma_f32_32x32x16_bf16 v[48:63], v[238:241], v[208:211], v[48:63]
	s_waitcnt lgkmcnt(2)
	v_mfma_f32_32x32x16_bf16 v[32:47], v[246:249], v[208:211], v[32:47]
	s_waitcnt lgkmcnt(1)
	v_mfma_f32_32x32x16_bf16 v[16:31], v[200:203], v[208:211], v[16:31]
	v_add_u32_e32 v238, v250, v235
	v_add_u32_e32 v239, v251, v235
	v_add_u32_e32 v240, v250, v236
	v_add_u32_e32 v241, v251, v236
	v_add_u32_e32 v250, v250, v237
	v_add_u32_e32 v251, v251, v237
	s_waitcnt vmcnt(15)
	ds_write_b128 v252, v[96:99]
	s_waitcnt vmcnt(14)
	ds_write_b128 v177, v[100:103]
	s_waitcnt vmcnt(13)
	ds_write_b128 v238, v[104:107]
	s_waitcnt vmcnt(12)
	ds_write_b128 v239, v[108:111]
	s_waitcnt vmcnt(11)
	ds_write_b128 v240, v[112:115]
	s_waitcnt vmcnt(10)
	ds_write_b128 v241, v[116:119]
	s_waitcnt vmcnt(9)
	ds_write_b128 v250, v[120:123]
	s_waitcnt vmcnt(8)
	ds_write_b128 v251, v[124:127]
	s_waitcnt lgkmcnt(8)
	v_mfma_f32_32x32x16_bf16 v[0:15], v[204:207], v[208:211], v[0:15]
	s_waitcnt lgkmcnt(0)
	s_barrier
	s_and_b32 s77, s76, 1
	s_mul_i32 s78, s77, 0x4800
	s_add_u32 s100, s58, 0x80
	s_addc_u32 s101, s59, 0
	v_lshl_add_u64 v[96:97], v[160:161], 0, s[100:101]
	v_lshl_add_u64 v[100:101], v[168:169], 0, s[100:101]
	v_lshl_add_u64 v[104:105], v[162:163], 0, s[100:101]
	v_lshl_add_u64 v[108:109], v[170:171], 0, s[100:101]
	v_lshl_add_u64 v[112:113], v[164:165], 0, s[100:101]
	v_lshl_add_u64 v[116:117], v[172:173], 0, s[100:101]
	v_lshl_add_u64 v[120:121], v[166:167], 0, s[100:101]
	v_lshl_add_u64 v[124:125], v[174:175], 0, s[100:101]
	v_add3_u32 v197, s78, v232, v231
	global_load_dwordx4 v[96:99], v[96:97], off
	s_nop 0
	global_load_dwordx4 v[100:103], v[100:101], off
	s_nop 0
	global_load_dwordx4 v[104:107], v[104:105], off
	s_nop 0
	global_load_dwordx4 v[108:111], v[108:109], off
	s_nop 0
	global_load_dwordx4 v[112:115], v[112:113], off
	s_nop 0
	global_load_dwordx4 v[116:119], v[116:117], off
	s_nop 0
	global_load_dwordx4 v[120:123], v[120:121], off
	s_nop 0
	global_load_dwordx4 v[124:127], v[124:125], off
	v_add3_u32 v198, s78, v234, v231
	ds_read_b128 v[242:245], v198 offset:36864
	ds_read_b128 v[238:241], v197
	ds_read_b128 v[246:249], v197 offset:4608
	ds_read_b128 v[200:203], v197 offset:9216
	ds_read_b128 v[204:207], v197 offset:13824
	s_waitcnt lgkmcnt(3)
	v_mfma_f32_32x32x16_bf16 v[48:63], v[238:241], v[242:245], v[48:63]
	ds_read_b128 v[208:211], v198 offset:36896
	ds_read_b128 v[238:241], v197 offset:32
	s_add_i32 s76, s76, 1
	s_xor_b32 s79, s77, 1
	s_xor_b32 s80, s77, 3
	s_mul_i32 s77, s79, 0x4800
	s_add_u32 s58, s58, 0x80
	s_mul_i32 s78, s80, 0x4800
	s_waitcnt lgkmcnt(4)
	v_mfma_f32_32x32x16_bf16 v[32:47], v[246:249], v[242:245], v[32:47]
	ds_read_b128 v[246:249], v197 offset:4640
	v_or_b32_e32 v250, s77, v128
	s_addc_u32 s59, s59, 0
	v_or_b32_e32 v251, s78, v128
	v_add_u32_e32 v252, v250, v233
	s_cmpk_lg_i32 s58, 0x700
	v_add_u32_e32 v177, v251, v233
	s_waitcnt lgkmcnt(4)
	v_mfma_f32_32x32x16_bf16 v[16:31], v[200:203], v[242:245], v[16:31]
	ds_read_b128 v[200:203], v197 offset:9248
	s_waitcnt lgkmcnt(4)
	v_mfma_f32_32x32x16_bf16 v[0:15], v[204:207], v[242:245], v[0:15]
	ds_read_b128 v[204:207], v197 offset:13856
	s_waitcnt lgkmcnt(3)
	v_mfma_f32_32x32x16_bf16 v[48:63], v[238:241], v[208:211], v[48:63]
	ds_read_b128 v[242:245], v198 offset:36928
	ds_read_b128 v[238:241], v197 offset:64
	s_waitcnt lgkmcnt(4)
	v_mfma_f32_32x32x16_bf16 v[32:47], v[246:249], v[208:211], v[32:47]
	ds_read_b128 v[246:249], v197 offset:4672
	s_waitcnt lgkmcnt(4)
	v_mfma_f32_32x32x16_bf16 v[16:31], v[200:203], v[208:211], v[16:31]
	ds_read_b128 v[200:203], v197 offset:9280
	s_waitcnt lgkmcnt(4)
	v_mfma_f32_32x32x16_bf16 v[0:15], v[204:207], v[208:211], v[0:15]
	ds_read_b128 v[204:207], v197 offset:13888
	s_waitcnt lgkmcnt(3)
	v_mfma_f32_32x32x16_bf16 v[48:63], v[238:241], v[242:245], v[48:63]
	ds_read_b128 v[208:211], v198 offset:36960
	ds_read_b128 v[238:241], v197 offset:96
	s_waitcnt lgkmcnt(4)
	v_mfma_f32_32x32x16_bf16 v[32:47], v[246:249], v[242:245], v[32:47]
	ds_read_b128 v[246:249], v197 offset:4704
	s_waitcnt lgkmcnt(4)
	v_mfma_f32_32x32x16_bf16 v[16:31], v[200:203], v[242:245], v[16:31]
	ds_read_b128 v[200:203], v197 offset:9312
	s_waitcnt lgkmcnt(4)
	v_mfma_f32_32x32x16_bf16 v[0:15], v[204:207], v[242:245], v[0:15]
	ds_read_b128 v[204:207], v197 offset:13920
	s_waitcnt lgkmcnt(3)
	v_mfma_f32_32x32x16_bf16 v[48:63], v[238:241], v[208:211], v[48:63]
	s_waitcnt lgkmcnt(2)
	v_mfma_f32_32x32x16_bf16 v[32:47], v[246:249], v[208:211], v[32:47]
	s_waitcnt lgkmcnt(1)
	v_mfma_f32_32x32x16_bf16 v[16:31], v[200:203], v[208:211], v[16:31]
	v_add_u32_e32 v238, v250, v235
	v_add_u32_e32 v239, v251, v235
	v_add_u32_e32 v240, v250, v236
	v_add_u32_e32 v241, v251, v236
	v_add_u32_e32 v250, v250, v237
	v_add_u32_e32 v251, v251, v237
	s_waitcnt vmcnt(15)
	ds_write_b128 v252, v[64:67]
	s_waitcnt vmcnt(14)
	ds_write_b128 v177, v[68:71]
	s_waitcnt vmcnt(13)
	ds_write_b128 v238, v[72:75]
	s_waitcnt vmcnt(12)
	ds_write_b128 v239, v[76:79]
	s_waitcnt vmcnt(11)
	ds_write_b128 v240, v[80:83]
	s_waitcnt vmcnt(10)
	ds_write_b128 v241, v[84:87]
	s_waitcnt vmcnt(9)
	ds_write_b128 v250, v[88:91]
	s_waitcnt vmcnt(8)
	ds_write_b128 v251, v[92:95]
	s_waitcnt lgkmcnt(8)
	v_mfma_f32_32x32x16_bf16 v[0:15], v[204:207], v[208:211], v[0:15]
	s_waitcnt lgkmcnt(0)
	s_barrier
	s_cbranch_scc1 .LBB0_1004
	s_and_b32 s77, s76, 1
	s_mul_i32 s78, s77, 0x4800
	v_lshl_add_u64 v[250:251], v[130:131], 0, s[98:99]
	v_add3_u32 v197, s78, v232, v231
	v_lshl_add_u64 v[64:65], v[250:251], 0, v[136:137]
	global_load_dwordx4 v[64:67], v[64:65], off
	s_nop 0
	v_lshl_add_u64 v[68:69], v[250:251], 0, v[138:139]
	global_load_dwordx4 v[68:71], v[68:69], off
	s_nop 0
	v_lshl_add_u64 v[72:73], v[250:251], 0, v[140:141]
	global_load_dwordx4 v[72:75], v[72:73], off
	s_nop 0
	v_lshl_add_u64 v[76:77], v[250:251], 0, v[142:143]
	global_load_dwordx4 v[76:79], v[76:77], off
	s_nop 0
	v_lshl_add_u64 v[80:81], v[250:251], 0, v[144:145]
	global_load_dwordx4 v[80:83], v[80:81], off
	s_nop 0
	v_lshl_add_u64 v[84:85], v[250:251], 0, v[146:147]
	global_load_dwordx4 v[84:87], v[84:85], off
	s_nop 0
	v_lshl_add_u64 v[88:89], v[250:251], 0, v[148:149]
	global_load_dwordx4 v[88:91], v[88:89], off
	s_nop 0
	v_lshl_add_u64 v[92:93], v[250:251], 0, v[150:151]
	global_load_dwordx4 v[92:95], v[92:93], off
	v_add3_u32 v198, s78, v234, v231
	ds_read_b128 v[242:245], v198 offset:36864
	ds_read_b128 v[238:241], v197
	ds_read_b128 v[246:249], v197 offset:4608
	ds_read_b128 v[200:203], v197 offset:9216
	ds_read_b128 v[204:207], v197 offset:13824
	s_waitcnt lgkmcnt(3)
	v_mfma_f32_32x32x16_bf16 v[48:63], v[238:241], v[242:245], v[48:63]
	ds_read_b128 v[208:211], v198 offset:36896
	ds_read_b128 v[238:241], v197 offset:32
	s_add_i32 s76, s76, 1
	s_xor_b32 s79, s77, 1
	s_xor_b32 s80, s77, 3
	s_mul_i32 s77, s79, 0x4800
	s_add_u32 s58, s58, 0x80
	s_mul_i32 s78, s80, 0x4800
	s_waitcnt lgkmcnt(4)
	v_mfma_f32_32x32x16_bf16 v[32:47], v[246:249], v[242:245], v[32:47]
	ds_read_b128 v[246:249], v197 offset:4640
	v_or_b32_e32 v250, s77, v128
	s_addc_u32 s59, s59, 0
	v_or_b32_e32 v251, s78, v128
	v_add_u32_e32 v252, v250, v233
	s_cmpk_lg_i32 s58, 0x780
	v_add_u32_e32 v177, v251, v233
	s_waitcnt lgkmcnt(4)
	v_mfma_f32_32x32x16_bf16 v[16:31], v[200:203], v[242:245], v[16:31]
	ds_read_b128 v[200:203], v197 offset:9248
	s_waitcnt lgkmcnt(4)
	v_mfma_f32_32x32x16_bf16 v[0:15], v[204:207], v[242:245], v[0:15]
	ds_read_b128 v[204:207], v197 offset:13856
	s_waitcnt lgkmcnt(3)
	v_mfma_f32_32x32x16_bf16 v[48:63], v[238:241], v[208:211], v[48:63]
	ds_read_b128 v[242:245], v198 offset:36928
	ds_read_b128 v[238:241], v197 offset:64
	s_waitcnt lgkmcnt(4)
	v_mfma_f32_32x32x16_bf16 v[32:47], v[246:249], v[208:211], v[32:47]
	ds_read_b128 v[246:249], v197 offset:4672
	s_waitcnt lgkmcnt(4)
	v_mfma_f32_32x32x16_bf16 v[16:31], v[200:203], v[208:211], v[16:31]
	ds_read_b128 v[200:203], v197 offset:9280
	s_waitcnt lgkmcnt(4)
	v_mfma_f32_32x32x16_bf16 v[0:15], v[204:207], v[208:211], v[0:15]
	ds_read_b128 v[204:207], v197 offset:13888
	s_waitcnt lgkmcnt(3)
	v_mfma_f32_32x32x16_bf16 v[48:63], v[238:241], v[242:245], v[48:63]
	ds_read_b128 v[208:211], v198 offset:36960
	ds_read_b128 v[238:241], v197 offset:96
	s_waitcnt lgkmcnt(4)
	v_mfma_f32_32x32x16_bf16 v[32:47], v[246:249], v[242:245], v[32:47]
	ds_read_b128 v[246:249], v197 offset:4704
	s_waitcnt lgkmcnt(4)
	v_mfma_f32_32x32x16_bf16 v[16:31], v[200:203], v[242:245], v[16:31]
	ds_read_b128 v[200:203], v197 offset:9312
	s_waitcnt lgkmcnt(4)
	v_mfma_f32_32x32x16_bf16 v[0:15], v[204:207], v[242:245], v[0:15]
	ds_read_b128 v[204:207], v197 offset:13920
	s_waitcnt lgkmcnt(3)
	v_mfma_f32_32x32x16_bf16 v[48:63], v[238:241], v[208:211], v[48:63]
	s_waitcnt lgkmcnt(2)
	v_mfma_f32_32x32x16_bf16 v[32:47], v[246:249], v[208:211], v[32:47]
	s_waitcnt lgkmcnt(1)
	v_mfma_f32_32x32x16_bf16 v[16:31], v[200:203], v[208:211], v[16:31]
	v_add_u32_e32 v238, v250, v235
	v_add_u32_e32 v239, v251, v235
	v_add_u32_e32 v240, v250, v236
	v_add_u32_e32 v241, v251, v236
	v_add_u32_e32 v250, v250, v237
	v_add_u32_e32 v251, v251, v237
	s_waitcnt vmcnt(15)
	ds_write_b128 v252, v[96:99]
	s_waitcnt vmcnt(14)
	ds_write_b128 v177, v[100:103]
	s_waitcnt vmcnt(13)
	ds_write_b128 v238, v[104:107]
	s_waitcnt vmcnt(12)
	ds_write_b128 v239, v[108:111]
	s_waitcnt vmcnt(11)
	ds_write_b128 v240, v[112:115]
	s_waitcnt vmcnt(10)
	ds_write_b128 v241, v[116:119]
	s_waitcnt vmcnt(9)
	ds_write_b128 v250, v[120:123]
	s_waitcnt vmcnt(8)
	ds_write_b128 v251, v[124:127]
	s_waitcnt lgkmcnt(8)
	v_mfma_f32_32x32x16_bf16 v[0:15], v[204:207], v[208:211], v[0:15]
	s_waitcnt lgkmcnt(0)
	s_barrier
	v_or_b32_e32 v197, 0x61, v193
	v_or_b32_e32 v198, 0x62, v193
	v_or_b32_e32 v199, 0x63, v193
	v_or_b32_e32 v200, 0x68, v193
	v_or_b32_e32 v201, 0x69, v193
	v_or_b32_e32 v202, 0x6a, v193
	v_or_b32_e32 v203, 0x6b, v193
	v_or_b32_e32 v204, 0x70, v193
	v_or_b32_e32 v205, 0x71, v193
	v_or_b32_e32 v206, 0x72, v193
	v_or_b32_e32 v207, 0x73, v193
	v_or_b32_e32 v208, 0x78, v193
	v_or_b32_e32 v209, 0x79, v193
	v_or_b32_e32 v210, 0x7a, v193
	v_or_b32_e32 v211, 0x7b, v193
	v_add_u32_e32 v250, v232, v231
	v_add_u32_e32 v251, v234, v231
	s_mov_b32 s80, 1
	s_mov_b64 s[58:59], 0
	ds_read_b128 v[238:241], v251 offset:55296
	ds_read_b128 v[112:115], v250 offset:18432
	ds_read_b128 v[116:119], v250 offset:23040
	ds_read_b128 v[120:123], v250 offset:27648
	ds_read_b128 v[124:127], v250 offset:32256
	s_waitcnt lgkmcnt(3)
	v_mfma_f32_32x32x16_bf16 v[48:63], v[112:115], v[238:241], v[48:63]
	ds_read_b128 v[100:103], v251 offset:55328
	ds_read_b128 v[112:115], v250 offset:18464
	s_waitcnt lgkmcnt(4)
	v_mfma_f32_32x32x16_bf16 v[32:47], v[116:119], v[238:241], v[32:47]
	ds_read_b128 v[116:119], v250 offset:23072
	s_waitcnt lgkmcnt(4)
	v_mfma_f32_32x32x16_bf16 v[16:31], v[120:123], v[238:241], v[16:31]
	ds_read_b128 v[120:123], v250 offset:27680
	s_waitcnt lgkmcnt(4)
	v_mfma_f32_32x32x16_bf16 v[0:15], v[124:127], v[238:241], v[0:15]
	ds_read_b128 v[124:127], v250 offset:32288
	s_waitcnt lgkmcnt(3)
	v_mfma_f32_32x32x16_bf16 v[48:63], v[112:115], v[100:103], v[48:63]
	ds_read_b128 v[238:241], v251 offset:55360
	ds_read_b128 v[112:115], v250 offset:18496
	s_waitcnt lgkmcnt(4)
	v_mfma_f32_32x32x16_bf16 v[32:47], v[116:119], v[100:103], v[32:47]
	ds_read_b128 v[116:119], v250 offset:23104
	s_waitcnt lgkmcnt(4)
	v_mfma_f32_32x32x16_bf16 v[16:31], v[120:123], v[100:103], v[16:31]
	ds_read_b128 v[120:123], v250 offset:27712
	s_waitcnt lgkmcnt(4)
	v_mfma_f32_32x32x16_bf16 v[0:15], v[124:127], v[100:103], v[0:15]
	ds_read_b128 v[124:127], v250 offset:32320
	s_waitcnt lgkmcnt(3)
	v_mfma_f32_32x32x16_bf16 v[48:63], v[112:115], v[238:241], v[48:63]
	ds_read_b128 v[100:103], v251 offset:55392
	ds_read_b128 v[112:115], v250 offset:18528
	s_waitcnt lgkmcnt(4)
	v_mfma_f32_32x32x16_bf16 v[32:47], v[116:119], v[238:241], v[32:47]
	ds_read_b128 v[96:99], v250 offset:23136
	s_waitcnt lgkmcnt(4)
	v_mfma_f32_32x32x16_bf16 v[16:31], v[120:123], v[238:241], v[16:31]
	ds_read_b128 v[104:107], v250 offset:27744
	s_waitcnt lgkmcnt(4)
	v_mfma_f32_32x32x16_bf16 v[0:15], v[124:127], v[238:241], v[0:15]
	ds_read_b128 v[108:111], v250 offset:32352
	s_waitcnt lgkmcnt(3)
	v_mfma_f32_32x32x16_bf16 v[48:63], v[112:115], v[100:103], v[48:63]
	s_waitcnt lgkmcnt(0)
	s_barrier
	s_waitcnt vmcnt(0)
	ds_write_b128 v212, v[64:67]
	ds_write_b128 v213, v[68:71]
	ds_write_b128 v214, v[72:75]
	ds_write_b128 v215, v[76:79]
	ds_write_b128 v216, v[80:83]
	ds_write_b128 v217, v[84:87]
	ds_write_b128 v218, v[88:91]
	ds_write_b128 v219, v[92:95]
	s_waitcnt lgkmcnt(0)
	s_barrier
	ds_read2_b64 v[64:67], v196 offset1:2
	v_cvt_pk_bf16_f32 v80, v48, v49
	v_cvt_pk_bf16_f32 v81, v50, v51
	v_cvt_pk_bf16_f32 v82, v52, v53
	v_cvt_pk_bf16_f32 v83, v54, v55
	ds_read2_b64 v[48:51], v196 offset0:4 offset1:6
	v_cvt_pk_bf16_f32 v56, v56, v57
	s_waitcnt lgkmcnt(1)
	v_mfma_f32_32x32x16_bf16 v[64:79], v[64:67], v[80:83], 0
	v_cvt_pk_bf16_f32 v57, v58, v59
	v_cvt_pk_bf16_f32 v58, v60, v61
	v_cvt_pk_bf16_f32 v59, v62, v63
	v_add_u32_e32 v94, 0x4000, v196
	ds_read2_b64 v[90:93], v94 offset0:132 offset1:134
	v_mfma_f32_32x32x16_bf16 v[32:47], v[96:99], v[100:103], v[32:47]
	s_waitcnt lgkmcnt(1)
	v_mfma_f32_32x32x16_bf16 v[64:79], v[48:51], v[56:59], v[64:79]
	ds_read2_b64 v[48:51], v196 offset0:8 offset1:10
	s_nop 8
	v_cvt_pk_bf16_f32 v52, v32, v33
	v_cvt_pk_bf16_f32 v53, v34, v35
	v_cvt_pk_bf16_f32 v54, v36, v37
	v_cvt_pk_bf16_f32 v55, v38, v39
	ds_read2_b64 v[32:35], v196 offset0:12 offset1:14
	s_waitcnt lgkmcnt(1)
	v_mfma_f32_32x32x16_bf16 v[64:79], v[48:51], v[52:55], v[64:79]
	v_cvt_pk_bf16_f32 v48, v40, v41
	v_cvt_pk_bf16_f32 v49, v42, v43
	v_cvt_pk_bf16_f32 v50, v44, v45
	v_cvt_pk_bf16_f32 v51, v46, v47
	v_mfma_f32_32x32x16_bf16 v[16:31], v[104:107], v[100:103], v[16:31]
	s_waitcnt lgkmcnt(0)
	v_mfma_f32_32x32x16_bf16 v[64:79], v[32:35], v[48:51], v[64:79]
	ds_read2_b64 v[32:35], v196 offset0:16 offset1:18
	s_nop 8
	v_cvt_pk_bf16_f32 v44, v16, v17
	v_cvt_pk_bf16_f32 v45, v18, v19
	v_cvt_pk_bf16_f32 v46, v20, v21
	v_cvt_pk_bf16_f32 v47, v22, v23
	ds_read2_b64 v[16:19], v196 offset0:20 offset1:22
	v_cvt_pk_bf16_f32 v40, v24, v25
	s_waitcnt lgkmcnt(1)
	v_mfma_f32_32x32x16_bf16 v[64:79], v[32:35], v[44:47], v[64:79]
	v_cvt_pk_bf16_f32 v41, v26, v27
	v_cvt_pk_bf16_f32 v42, v28, v29
	v_cvt_pk_bf16_f32 v43, v30, v31
	v_add_u32_e32 v24, 0x2000, v196
	v_or_b32_e32 v22, 9, v193
	v_mfma_f32_32x32x16_bf16 v[0:15], v[108:111], v[100:103], v[0:15]
	v_add_u32_e32 v100, 0x6000, v196
	s_waitcnt lgkmcnt(0)
	v_mfma_f32_32x32x16_bf16 v[64:79], v[16:19], v[40:43], v[64:79]
	ds_read2_b64 v[16:19], v196 offset0:24 offset1:26
	s_nop 7
	v_cvt_pk_bf16_f32 v36, v0, v1
	v_cvt_pk_bf16_f32 v37, v2, v3
	v_cvt_pk_bf16_f32 v38, v4, v5
	v_cvt_pk_bf16_f32 v39, v6, v7
	ds_read2_b64 v[0:3], v196 offset0:28 offset1:30
	v_cvt_pk_bf16_f32 v32, v8, v9
	s_waitcnt lgkmcnt(1)
	v_mfma_f32_32x32x16_bf16 v[64:79], v[16:19], v[36:39], v[64:79]
	v_cvt_pk_bf16_f32 v33, v10, v11
	v_cvt_pk_bf16_f32 v34, v12, v13
	v_cvt_pk_bf16_f32 v35, v14, v15
	v_or_b32_e32 v6, 3, v193
	ds_read2_b64 v[16:19], v24 offset0:68 offset1:70
	s_waitcnt lgkmcnt(1)
	v_mfma_f32_32x32x16_bf16 v[64:79], v[0:3], v[32:35], v[64:79]
	v_or_b32_e32 v2, 1, v193
	s_nop 10
	v_ashrrev_i32_e32 v1, 31, v64
	v_and_b32_e32 v0, 0xffffff80, v64
	v_and_b32_e32 v1, 0x7fffffff, v1
	v_bitop3_b32 v60, v0, v1, v193 bitop3:0x36
	v_ashrrev_i32_e32 v1, 31, v65
	v_and_b32_e32 v0, 0xffffff80, v65
	v_and_b32_e32 v1, 0x7fffffff, v1
	v_bitop3_b32 v61, v0, v1, v2 bitop3:0x36
	v_ashrrev_i32_e32 v1, 31, v66
	v_and_b32_e32 v0, 0xffffff80, v66
	v_and_b32_e32 v1, 0x7fffffff, v1
	v_or_b32_e32 v2, 2, v193
	v_bitop3_b32 v62, v0, v1, v2 bitop3:0x36
	ds_read2_b64 v[0:3], v24 offset0:64 offset1:66
	v_ashrrev_i32_e32 v5, 31, v67
	v_and_b32_e32 v4, 0xffffff80, v67
	v_and_b32_e32 v5, 0x7fffffff, v5
	v_bitop3_b32 v63, v4, v5, v6 bitop3:0x36
	v_ashrrev_i32_e32 v5, 31, v68
	v_and_b32_e32 v4, 0xffffff80, v68
	v_and_b32_e32 v5, 0x7fffffff, v5
	v_or_b32_e32 v6, 8, v193
	v_bitop3_b32 v64, v4, v5, v6 bitop3:0x36
	s_waitcnt lgkmcnt(0)
	v_mfma_f32_32x32x16_bf16 v[0:15], v[0:3], v[80:83], 0
	v_ashrrev_i32_e32 v21, 31, v69
	v_and_b32_e32 v20, 0xffffff80, v69
	v_and_b32_e32 v21, 0x7fffffff, v21
	v_bitop3_b32 v68, v20, v21, v22 bitop3:0x36
	v_ashrrev_i32_e32 v20, 31, v70
	v_and_b32_e32 v26, 0x7fffffff, v20
	ds_read2_b64 v[20:23], v24 offset0:72 offset1:74
	v_mfma_f32_32x32x16_bf16 v[0:15], v[16:19], v[56:59], v[0:15]
	v_and_b32_e32 v25, 0xffffff80, v70
	v_or_b32_e32 v16, 10, v193
	v_ashrrev_i32_e32 v17, 31, v71
	v_bitop3_b32 v69, v25, v26, v16 bitop3:0x36
	v_and_b32_e32 v16, 0xffffff80, v71
	v_and_b32_e32 v17, 0x7fffffff, v17
	v_or_b32_e32 v18, 11, v193
	v_bitop3_b32 v70, v16, v17, v18 bitop3:0x36
	ds_read2_b64 v[16:19], v24 offset0:76 offset1:78
	s_waitcnt lgkmcnt(1)
	v_mfma_f32_32x32x16_bf16 v[0:15], v[20:23], v[52:55], v[0:15]
	v_ashrrev_i32_e32 v20, 31, v72
	v_and_b32_e32 v25, 0xffffff80, v72
	v_and_b32_e32 v20, 0x7fffffff, v20
	v_or_b32_e32 v21, 16, v193
	v_bitop3_b32 v71, v25, v20, v21 bitop3:0x36
	v_ashrrev_i32_e32 v20, 31, v73
	v_and_b32_e32 v26, 0x7fffffff, v20
	ds_read2_b64 v[20:23], v24 offset0:80 offset1:82
	s_waitcnt lgkmcnt(1)
	v_mfma_f32_32x32x16_bf16 v[0:15], v[16:19], v[48:51], v[0:15]
	v_and_b32_e32 v25, 0xffffff80, v73
	v_or_b32_e32 v16, 17, v193
	v_ashrrev_i32_e32 v17, 31, v74
	v_bitop3_b32 v72, v25, v26, v16 bitop3:0x36
	v_and_b32_e32 v16, 0xffffff80, v74
	v_and_b32_e32 v17, 0x7fffffff, v17
	v_or_b32_e32 v18, 18, v193
	v_bitop3_b32 v74, v16, v17, v18 bitop3:0x36
	ds_read2_b64 v[16:19], v24 offset0:84 offset1:86
	s_waitcnt lgkmcnt(1)
	v_mfma_f32_32x32x16_bf16 v[0:15], v[20:23], v[44:47], v[0:15]
	v_ashrrev_i32_e32 v20, 31, v75
	v_and_b32_e32 v25, 0xffffff80, v75
	v_and_b32_e32 v20, 0x7fffffff, v20
	v_or_b32_e32 v21, 19, v193
	v_bitop3_b32 v84, v25, v20, v21 bitop3:0x36
	v_ashrrev_i32_e32 v20, 31, v76
	v_and_b32_e32 v26, 0x7fffffff, v20
	ds_read2_b64 v[20:23], v24 offset0:88 offset1:90
	s_waitcnt lgkmcnt(1)
	v_mfma_f32_32x32x16_bf16 v[0:15], v[16:19], v[40:43], v[0:15]
	v_and_b32_e32 v25, 0xffffff80, v76
	v_or_b32_e32 v16, 24, v193
	v_ashrrev_i32_e32 v17, 31, v77
	v_bitop3_b32 v85, v25, v26, v16 bitop3:0x36
	v_and_b32_e32 v16, 0xffffff80, v77
	v_and_b32_e32 v17, 0x7fffffff, v17
	v_or_b32_e32 v18, 25, v193
	v_bitop3_b32 v86, v16, v17, v18 bitop3:0x36
	ds_read2_b64 v[16:19], v24 offset0:92 offset1:94
	s_waitcnt lgkmcnt(1)
	v_mfma_f32_32x32x16_bf16 v[0:15], v[20:23], v[36:39], v[0:15]
	v_ashrrev_i32_e32 v20, 31, v78
	v_and_b32_e32 v25, 0xffffff80, v78
	v_and_b32_e32 v20, 0x7fffffff, v20
	v_or_b32_e32 v21, 26, v193
	v_bitop3_b32 v87, v25, v20, v21 bitop3:0x36
	v_ashrrev_i32_e32 v21, 31, v79
	v_and_b32_e32 v20, 0xffffff80, v79
	s_waitcnt lgkmcnt(0)
	v_mfma_f32_32x32x16_bf16 v[0:15], v[16:19], v[32:35], v[0:15]
	v_or_b32_e32 v17, 32, v193
	v_or_b32_e32 v18, 35, v193
	v_and_b32_e32 v21, 0x7fffffff, v21
	v_or_b32_e32 v22, 27, v193
	v_bitop3_b32 v88, v20, v21, v22 bitop3:0x36
	s_nop 6
	v_and_b32_e32 v16, 0xffffff80, v0
	v_ashrrev_i32_e32 v0, 31, v0
	v_and_b32_e32 v0, 0x7fffffff, v0
	v_bitop3_b32 v65, v16, v0, v17 bitop3:0x36
	v_and_b32_e32 v0, 0xffffff80, v1
	v_ashrrev_i32_e32 v1, 31, v1
	v_and_b32_e32 v1, 0x7fffffff, v1
	v_or_b32_e32 v16, 33, v193
	v_bitop3_b32 v66, v0, v1, v16 bitop3:0x36
	v_ashrrev_i32_e32 v1, 31, v2
	v_and_b32_e32 v0, 0xffffff80, v2
	v_and_b32_e32 v1, 0x7fffffff, v1
	v_or_b32_e32 v2, 34, v193
	v_bitop3_b32 v67, v0, v1, v2 bitop3:0x36
	v_and_b32_e32 v16, 0xffffff80, v3
	v_ashrrev_i32_e32 v17, 31, v3
	ds_read2_b64 v[0:3], v94 offset0:128 offset1:130
	v_and_b32_e32 v17, 0x7fffffff, v17
	v_bitop3_b32 v73, v16, v17, v18 bitop3:0x36
	v_and_b32_e32 v16, 0xffffff80, v4
	v_ashrrev_i32_e32 v4, 31, v4
	v_and_b32_e32 v4, 0x7fffffff, v4
	v_or_b32_e32 v17, 40, v193
	v_bitop3_b32 v75, v16, v4, v17 bitop3:0x36
	s_waitcnt lgkmcnt(0)
	v_mfma_f32_32x32x16_bf16 v[16:31], v[0:3], v[80:83], 0
	v_ashrrev_i32_e32 v0, 31, v5
	v_and_b32_e32 v4, 0xffffff80, v5
	v_and_b32_e32 v0, 0x7fffffff, v0
	v_or_b32_e32 v1, 41, v193
	v_bitop3_b32 v76, v4, v0, v1 bitop3:0x36
	v_ashrrev_i32_e32 v0, 31, v6
	v_and_b32_e32 v5, 0x7fffffff, v0
	ds_read2_b64 v[0:3], v94 offset0:136 offset1:138
	v_mfma_f32_32x32x16_bf16 v[16:31], v[90:93], v[56:59], v[16:31]
	v_and_b32_e32 v4, 0xffffff80, v6
	v_or_b32_e32 v6, 42, v193
	v_bitop3_b32 v77, v4, v5, v6 bitop3:0x36
	v_ashrrev_i32_e32 v5, 31, v7
	v_and_b32_e32 v4, 0xffffff80, v7
	v_and_b32_e32 v5, 0x7fffffff, v5
	v_or_b32_e32 v6, 43, v193
	v_bitop3_b32 v78, v4, v5, v6 bitop3:0x36
	ds_read2_b64 v[4:7], v94 offset0:140 offset1:142
	s_waitcnt lgkmcnt(1)
	v_mfma_f32_32x32x16_bf16 v[16:31], v[0:3], v[52:55], v[16:31]
	v_ashrrev_i32_e32 v0, 31, v8
	v_and_b32_e32 v79, 0xffffff80, v8
	v_and_b32_e32 v0, 0x7fffffff, v0
	v_or_b32_e32 v1, 48, v193
	v_bitop3_b32 v79, v79, v0, v1 bitop3:0x36
	v_ashrrev_i32_e32 v0, 31, v9
	v_and_b32_e32 v8, 0xffffff80, v9
	v_and_b32_e32 v9, 0x7fffffff, v0
	ds_read2_b64 v[0:3], v94 offset0:144 offset1:146
	s_waitcnt lgkmcnt(1)
	v_mfma_f32_32x32x16_bf16 v[16:31], v[4:7], v[48:51], v[16:31]
	v_or_b32_e32 v4, 49, v193
	v_ashrrev_i32_e32 v5, 31, v10
	v_bitop3_b32 v89, v8, v9, v4 bitop3:0x36
	v_and_b32_e32 v4, 0xffffff80, v10
	v_and_b32_e32 v5, 0x7fffffff, v5
	v_or_b32_e32 v6, 50, v193
	v_bitop3_b32 v90, v4, v5, v6 bitop3:0x36
	ds_read2_b64 v[4:7], v94 offset0:148 offset1:150
	s_waitcnt lgkmcnt(1)
	v_mfma_f32_32x32x16_bf16 v[16:31], v[0:3], v[44:47], v[16:31]
	v_ashrrev_i32_e32 v0, 31, v11
	v_and_b32_e32 v8, 0xffffff80, v11
	v_and_b32_e32 v0, 0x7fffffff, v0
	v_or_b32_e32 v1, 51, v193
	v_bitop3_b32 v91, v8, v0, v1 bitop3:0x36
	v_ashrrev_i32_e32 v0, 31, v12
	v_and_b32_e32 v9, 0x7fffffff, v0
	ds_read2_b64 v[0:3], v94 offset0:152 offset1:154
	s_waitcnt lgkmcnt(1)
	v_mfma_f32_32x32x16_bf16 v[16:31], v[4:7], v[40:43], v[16:31]
	v_and_b32_e32 v8, 0xffffff80, v12
	v_or_b32_e32 v4, 56, v193
	v_ashrrev_i32_e32 v5, 31, v13
	v_bitop3_b32 v96, v8, v9, v4 bitop3:0x36
	v_and_b32_e32 v4, 0xffffff80, v13
	v_and_b32_e32 v5, 0x7fffffff, v5
	v_or_b32_e32 v6, 57, v193
	v_bitop3_b32 v97, v4, v5, v6 bitop3:0x36
	ds_read2_b64 v[4:7], v94 offset0:156 offset1:158
	s_waitcnt lgkmcnt(1)
	v_mfma_f32_32x32x16_bf16 v[16:31], v[0:3], v[36:39], v[16:31]
	v_ashrrev_i32_e32 v0, 31, v14
	v_and_b32_e32 v8, 0xffffff80, v14
	v_and_b32_e32 v0, 0x7fffffff, v0
	v_or_b32_e32 v1, 58, v193
	v_bitop3_b32 v98, v8, v0, v1 bitop3:0x36
	v_ashrrev_i32_e32 v1, 31, v15
	v_and_b32_e32 v0, 0xffffff80, v15
	s_waitcnt lgkmcnt(0)
	v_mfma_f32_32x32x16_bf16 v[16:31], v[4:7], v[32:35], v[16:31]
	v_and_b32_e32 v1, 0x7fffffff, v1
	v_or_b32_e32 v2, 59, v193
	v_bitop3_b32 v99, v0, v1, v2 bitop3:0x36
	v_or_b32_e32 v2, 64, v193
	v_or_b32_e32 v6, 0x43, v193
	ds_read2_b64 v[92:95], v100 offset0:196 offset1:198
	s_nop 5
	v_ashrrev_i32_e32 v1, 31, v16
	v_and_b32_e32 v0, 0xffffff80, v16
	v_and_b32_e32 v1, 0x7fffffff, v1
	v_bitop3_b32 v16, v0, v1, v2 bitop3:0x36
	v_ashrrev_i32_e32 v1, 31, v17
	v_and_b32_e32 v0, 0xffffff80, v17
	v_and_b32_e32 v1, 0x7fffffff, v1
	v_or_b32_e32 v2, 0x41, v193
	v_bitop3_b32 v17, v0, v1, v2 bitop3:0x36
	v_ashrrev_i32_e32 v1, 31, v18
	v_and_b32_e32 v0, 0xffffff80, v18
	v_and_b32_e32 v1, 0x7fffffff, v1
	v_or_b32_e32 v2, 0x42, v193
	v_bitop3_b32 v18, v0, v1, v2 bitop3:0x36
	ds_read2_b64 v[0:3], v100 offset0:192 offset1:194
	v_ashrrev_i32_e32 v5, 31, v19
	v_and_b32_e32 v4, 0xffffff80, v19
	v_and_b32_e32 v5, 0x7fffffff, v5
	v_bitop3_b32 v19, v4, v5, v6 bitop3:0x36
	v_ashrrev_i32_e32 v5, 31, v20
	v_and_b32_e32 v4, 0xffffff80, v20
	v_and_b32_e32 v5, 0x7fffffff, v5
	v_or_b32_e32 v6, 0x48, v193
	v_bitop3_b32 v20, v4, v5, v6 bitop3:0x36
	s_waitcnt lgkmcnt(0)
	v_mfma_f32_32x32x16_bf16 v[0:15], v[0:3], v[80:83], 0
	v_and_b32_e32 v101, 0xffffff80, v21
	v_ashrrev_i32_e32 v21, 31, v21
	v_and_b32_e32 v21, 0x7fffffff, v21
	v_or_b32_e32 v80, 0x49, v193
	v_bitop3_b32 v21, v101, v21, v80 bitop3:0x36
	ds_read2_b64 v[80:83], v100 offset0:200 offset1:202
	v_and_b32_e32 v101, 0xffffff80, v22
	v_mfma_f32_32x32x16_bf16 v[0:15], v[92:95], v[56:59], v[0:15]
	v_ashrrev_i32_e32 v22, 31, v22
	v_and_b32_e32 v22, 0x7fffffff, v22
	v_or_b32_e32 v56, 0x4a, v193
	v_bitop3_b32 v92, v101, v22, v56 bitop3:0x36
	v_and_b32_e32 v22, 0xffffff80, v23
	v_ashrrev_i32_e32 v23, 31, v23
	v_and_b32_e32 v23, 0x7fffffff, v23
	v_or_b32_e32 v56, 0x4b, v193
	v_bitop3_b32 v93, v22, v23, v56 bitop3:0x36
	ds_read2_b64 v[56:59], v100 offset0:204 offset1:206
	s_waitcnt lgkmcnt(1)
	v_mfma_f32_32x32x16_bf16 v[0:15], v[80:83], v[52:55], v[0:15]
	v_ashrrev_i32_e32 v23, 31, v24
	v_and_b32_e32 v22, 0xffffff80, v24
	v_and_b32_e32 v23, 0x7fffffff, v23
	v_or_b32_e32 v24, 0x50, v193
	v_bitop3_b32 v52, v22, v23, v24 bitop3:0x36
	v_ashrrev_i32_e32 v22, 31, v25
	v_and_b32_e32 v53, 0xffffff80, v25
	v_and_b32_e32 v54, 0x7fffffff, v22
	ds_read2_b64 v[22:25], v100 offset0:208 offset1:210
	s_waitcnt lgkmcnt(1)
	v_mfma_f32_32x32x16_bf16 v[0:15], v[56:59], v[48:51], v[0:15]
	v_or_b32_e32 v48, 0x51, v193
	v_bitop3_b32 v53, v53, v54, v48 bitop3:0x36
	v_and_b32_e32 v48, 0xffffff80, v26
	v_ashrrev_i32_e32 v26, 31, v26
	v_and_b32_e32 v26, 0x7fffffff, v26
	v_or_b32_e32 v49, 0x52, v193
	v_bitop3_b32 v54, v48, v26, v49 bitop3:0x36
	ds_read2_b64 v[48:51], v100 offset0:212 offset1:214
	s_waitcnt lgkmcnt(1)
	v_mfma_f32_32x32x16_bf16 v[0:15], v[22:25], v[44:47], v[0:15]
	v_ashrrev_i32_e32 v22, 31, v27
	v_and_b32_e32 v26, 0xffffff80, v27
	v_and_b32_e32 v22, 0x7fffffff, v22
	v_or_b32_e32 v23, 0x53, v193
	v_bitop3_b32 v44, v26, v22, v23 bitop3:0x36
	v_ashrrev_i32_e32 v22, 31, v28
	v_and_b32_e32 v27, 0x7fffffff, v22
	ds_read2_b64 v[22:25], v100 offset0:216 offset1:218
	s_waitcnt lgkmcnt(1)
	v_mfma_f32_32x32x16_bf16 v[0:15], v[48:51], v[40:43], v[0:15]
	v_and_b32_e32 v26, 0xffffff80, v28
	v_or_b32_e32 v28, 0x58, v193
	v_bitop3_b32 v40, v26, v27, v28 bitop3:0x36
	v_ashrrev_i32_e32 v27, 31, v29
	v_and_b32_e32 v26, 0xffffff80, v29
	v_and_b32_e32 v27, 0x7fffffff, v27
	v_or_b32_e32 v28, 0x59, v193
	v_bitop3_b32 v41, v26, v27, v28 bitop3:0x36
	ds_read2_b64 v[26:29], v100 offset0:220 offset1:222
	s_waitcnt lgkmcnt(1)
	v_mfma_f32_32x32x16_bf16 v[0:15], v[22:25], v[36:39], v[0:15]
	v_ashrrev_i32_e32 v22, 31, v30
	v_and_b32_e32 v42, 0xffffff80, v30
	v_and_b32_e32 v22, 0x7fffffff, v22
	v_or_b32_e32 v23, 0x5a, v193
	v_ashrrev_i32_e32 v24, 31, v31
	v_bitop3_b32 v22, v42, v22, v23 bitop3:0x36
	v_and_b32_e32 v23, 0xffffff80, v31
	s_waitcnt lgkmcnt(0)
	v_mfma_f32_32x32x16_bf16 v[0:15], v[26:29], v[32:35], v[0:15]
	v_and_b32_e32 v24, 0x7fffffff, v24
	v_or_b32_e32 v25, 0x5b, v193
	v_bitop3_b32 v23, v23, v24, v25 bitop3:0x36
	v_or_b32_e32 v25, 0x60, v193
	v_max_i32_e32 v26, v63, v62
	v_min_i32_e32 v27, v63, v62
	v_max_i32_e32 v28, v64, v68
	s_nop 4
	v_and_b32_e32 v24, 0xffffff80, v0
	v_ashrrev_i32_e32 v0, 31, v0
	v_and_b32_e32 v0, 0x7fffffff, v0
	v_bitop3_b32 v0, v24, v0, v25 bitop3:0x36
	v_and_b32_e32 v24, 0xffffff80, v1
	v_ashrrev_i32_e32 v1, 31, v1
	v_and_b32_e32 v1, 0x7fffffff, v1
	v_bitop3_b32 v1, v24, v1, v197 bitop3:0x36
	v_and_b32_e32 v24, 0xffffff80, v2
	v_ashrrev_i32_e32 v2, 31, v2
	v_and_b32_e32 v2, 0x7fffffff, v2
	v_bitop3_b32 v2, v24, v2, v198 bitop3:0x36
	v_and_b32_e32 v24, 0xffffff80, v3
	v_ashrrev_i32_e32 v3, 31, v3
	v_and_b32_e32 v3, 0x7fffffff, v3
	v_bitop3_b32 v3, v24, v3, v199 bitop3:0x36
	v_and_b32_e32 v24, 0xffffff80, v4
	v_ashrrev_i32_e32 v4, 31, v4
	v_and_b32_e32 v4, 0x7fffffff, v4
	v_bitop3_b32 v4, v24, v4, v200 bitop3:0x36
	v_and_b32_e32 v24, 0xffffff80, v5
	v_ashrrev_i32_e32 v5, 31, v5
	v_and_b32_e32 v5, 0x7fffffff, v5
	v_bitop3_b32 v5, v24, v5, v201 bitop3:0x36
	v_and_b32_e32 v24, 0xffffff80, v6
	v_ashrrev_i32_e32 v6, 31, v6
	v_and_b32_e32 v6, 0x7fffffff, v6
	v_bitop3_b32 v6, v24, v6, v202 bitop3:0x36
	v_and_b32_e32 v24, 0xffffff80, v7
	v_ashrrev_i32_e32 v7, 31, v7
	v_and_b32_e32 v7, 0x7fffffff, v7
	v_bitop3_b32 v7, v24, v7, v203 bitop3:0x36
	v_and_b32_e32 v24, 0xffffff80, v8
	v_ashrrev_i32_e32 v8, 31, v8
	v_and_b32_e32 v8, 0x7fffffff, v8
	v_bitop3_b32 v8, v24, v8, v204 bitop3:0x36
	v_and_b32_e32 v24, 0xffffff80, v9
	v_ashrrev_i32_e32 v9, 31, v9
	v_and_b32_e32 v9, 0x7fffffff, v9
	v_bitop3_b32 v9, v24, v9, v205 bitop3:0x36
	v_and_b32_e32 v24, 0xffffff80, v10
	v_ashrrev_i32_e32 v10, 31, v10
	v_and_b32_e32 v10, 0x7fffffff, v10
	v_bitop3_b32 v10, v24, v10, v206 bitop3:0x36
	v_and_b32_e32 v24, 0xffffff80, v11
	v_ashrrev_i32_e32 v11, 31, v11
	v_and_b32_e32 v11, 0x7fffffff, v11
	v_bitop3_b32 v11, v24, v11, v207 bitop3:0x36
	v_and_b32_e32 v24, 0xffffff80, v12
	v_ashrrev_i32_e32 v12, 31, v12
	v_and_b32_e32 v12, 0x7fffffff, v12
	v_bitop3_b32 v12, v24, v12, v208 bitop3:0x36
	v_and_b32_e32 v24, 0xffffff80, v13
	v_ashrrev_i32_e32 v13, 31, v13
	v_and_b32_e32 v13, 0x7fffffff, v13
	v_bitop3_b32 v13, v24, v13, v209 bitop3:0x36
	v_and_b32_e32 v24, 0xffffff80, v14
	v_ashrrev_i32_e32 v14, 31, v14
	v_and_b32_e32 v14, 0x7fffffff, v14
	v_bitop3_b32 v14, v24, v14, v210 bitop3:0x36
	v_and_b32_e32 v24, 0xffffff80, v15
	v_ashrrev_i32_e32 v15, 31, v15
	v_and_b32_e32 v15, 0x7fffffff, v15
	v_bitop3_b32 v15, v24, v15, v211 bitop3:0x36
	v_max_i32_e32 v24, v60, v61
	v_min_i32_e32 v25, v60, v61
	v_min_i32_e32 v29, v64, v68
	v_max_i32_e32 v30, v70, v69
	v_min_i32_e32 v31, v70, v69
	v_max_i32_e32 v32, v71, v72
	v_min_i32_e32 v33, v71, v72
	v_max_i32_e32 v34, v84, v74
	v_min_i32_e32 v35, v84, v74
	v_max_i32_e32 v36, v85, v86
	v_min_i32_e32 v37, v85, v86
	v_max_i32_e32 v38, v88, v87
	v_min_i32_e32 v39, v88, v87
	v_max_i32_e32 v51, v65, v66
	v_min_i32_e32 v55, v65, v66
	v_max_i32_e32 v56, v73, v67
	v_min_i32_e32 v57, v73, v67
	v_max_i32_e32 v58, v75, v76
	v_min_i32_e32 v59, v75, v76
	v_max_i32_e32 v60, v78, v77
	v_min_i32_e32 v61, v78, v77
	v_max_i32_e32 v62, v79, v89
	v_min_i32_e32 v63, v79, v89
	v_max_i32_e32 v64, v91, v90
	v_min_i32_e32 v65, v91, v90
	v_max_i32_e32 v66, v96, v97
	v_min_i32_e32 v67, v96, v97
	v_max_i32_e32 v68, v99, v98
	v_min_i32_e32 v69, v99, v98
	v_max_i32_e32 v78, v16, v17
	v_min_i32_e32 v16, v16, v17
	v_max_i32_e32 v17, v19, v18
	v_min_i32_e32 v18, v19, v18
	v_max_i32_e32 v19, v20, v21
	v_min_i32_e32 v20, v20, v21
	v_max_i32_e32 v21, v93, v92
	v_min_i32_e32 v79, v93, v92
	v_max_i32_e32 v80, v52, v53
	v_min_i32_e32 v52, v52, v53
	v_max_i32_e32 v53, v44, v54
	v_min_i32_e32 v44, v44, v54
	v_max_i32_e32 v54, v40, v41
	v_min_i32_e32 v40, v40, v41
	v_max_i32_e32 v41, v23, v22
	v_min_i32_e32 v22, v23, v22
	v_max_i32_e32 v88, v0, v1
	v_min_i32_e32 v0, v0, v1
	v_max_i32_e32 v1, v3, v2
	v_min_i32_e32 v2, v3, v2
	v_max_i32_e32 v3, v4, v5
	v_min_i32_e32 v4, v4, v5
	v_max_i32_e32 v5, v7, v6
	v_min_i32_e32 v6, v7, v6
	v_max_i32_e32 v7, v8, v9
	v_min_i32_e32 v8, v8, v9
	v_max_i32_e32 v9, v11, v10
	v_min_i32_e32 v10, v11, v10
	v_max_i32_e32 v11, v12, v13
	v_min_i32_e32 v12, v12, v13
	v_max_i32_e32 v13, v15, v14
	v_min_i32_e32 v14, v15, v14
	v_max_i32_e32 v42, v24, v27
	v_min_i32_e32 v24, v24, v27
	v_max_i32_e32 v27, v25, v26
	v_min_i32_e32 v25, v25, v26
	v_max_i32_e32 v26, v31, v28
	v_min_i32_e32 v28, v31, v28
	v_max_i32_e32 v31, v30, v29
	v_min_i32_e32 v29, v30, v29
	v_max_i32_e32 v30, v32, v35
	v_min_i32_e32 v32, v32, v35
	v_max_i32_e32 v35, v33, v34
	v_min_i32_e32 v33, v33, v34
	v_max_i32_e32 v34, v39, v36
	v_min_i32_e32 v36, v39, v36
	v_max_i32_e32 v39, v38, v37
	v_min_i32_e32 v37, v38, v37
	v_max_i32_e32 v70, v51, v57
	v_min_i32_e32 v51, v51, v57
	v_max_i32_e32 v57, v55, v56
	v_min_i32_e32 v55, v55, v56
	v_max_i32_e32 v56, v61, v58
	v_min_i32_e32 v58, v61, v58
	v_max_i32_e32 v61, v60, v59
	v_min_i32_e32 v59, v60, v59
	v_max_i32_e32 v60, v62, v65
	v_min_i32_e32 v62, v62, v65
	v_max_i32_e32 v65, v63, v64
	v_min_i32_e32 v63, v63, v64
	v_max_i32_e32 v64, v69, v66
	v_min_i32_e32 v66, v69, v66
	v_max_i32_e32 v69, v68, v67
	v_min_i32_e32 v67, v68, v67
	v_max_i32_e32 v23, v78, v18
	v_min_i32_e32 v18, v78, v18
	v_max_i32_e32 v78, v16, v17
	v_min_i32_e32 v16, v16, v17
	v_max_i32_e32 v17, v79, v19
	v_min_i32_e32 v19, v79, v19
	v_max_i32_e32 v79, v21, v20
	v_min_i32_e32 v20, v21, v20
	v_max_i32_e32 v21, v80, v44
	v_min_i32_e32 v44, v80, v44
	v_max_i32_e32 v80, v52, v53
	v_min_i32_e32 v52, v52, v53
	v_max_i32_e32 v53, v22, v54
	v_min_i32_e32 v22, v22, v54
	v_max_i32_e32 v54, v41, v40
	v_min_i32_e32 v40, v41, v40
	v_max_i32_e32 v15, v88, v2
	v_min_i32_e32 v2, v88, v2
	v_max_i32_e32 v88, v0, v1
	v_min_i32_e32 v0, v0, v1
	v_max_i32_e32 v1, v6, v3
	v_min_i32_e32 v3, v6, v3
	v_max_i32_e32 v6, v5, v4
	v_min_i32_e32 v4, v5, v4
	v_max_i32_e32 v5, v7, v10
	v_min_i32_e32 v7, v7, v10
	v_max_i32_e32 v10, v8, v9
	v_min_i32_e32 v8, v8, v9
	v_max_i32_e32 v9, v14, v11
	v_min_i32_e32 v11, v14, v11
	v_max_i32_e32 v14, v13, v12
	v_min_i32_e32 v12, v13, v12
	v_max_i32_e32 v38, v42, v27
	v_min_i32_e32 v27, v42, v27
	v_max_i32_e32 v42, v24, v25
	v_min_i32_e32 v24, v24, v25
	v_max_i32_e32 v25, v29, v28
	v_min_i32_e32 v28, v29, v28
	v_max_i32_e32 v29, v31, v26
	v_min_i32_e32 v26, v31, v26
	v_max_i32_e32 v31, v30, v35
	v_min_i32_e32 v30, v30, v35
	v_max_i32_e32 v35, v32, v33
	v_min_i32_e32 v32, v32, v33
	v_max_i32_e32 v33, v37, v36
	v_min_i32_e32 v36, v37, v36
	v_max_i32_e32 v37, v39, v34
	v_min_i32_e32 v34, v39, v34
	v_max_i32_e32 v68, v70, v57
	v_min_i32_e32 v57, v70, v57
	v_max_i32_e32 v70, v51, v55
	v_min_i32_e32 v51, v51, v55
	v_max_i32_e32 v55, v59, v58
	v_min_i32_e32 v58, v59, v58
	v_max_i32_e32 v59, v61, v56
	v_min_i32_e32 v56, v61, v56
	v_max_i32_e32 v61, v60, v65
	v_min_i32_e32 v60, v60, v65
	v_max_i32_e32 v65, v62, v63
	v_min_i32_e32 v62, v62, v63
	v_max_i32_e32 v63, v67, v66
	v_min_i32_e32 v66, v67, v66
	v_max_i32_e32 v67, v69, v64
	v_min_i32_e32 v64, v69, v64
	v_max_i32_e32 v41, v23, v78
	v_min_i32_e32 v23, v23, v78
	v_max_i32_e32 v78, v18, v16
	v_min_i32_e32 v16, v18, v16
	v_max_i32_e32 v18, v20, v19
	v_min_i32_e32 v19, v20, v19
	v_max_i32_e32 v20, v79, v17
	v_min_i32_e32 v17, v79, v17
	v_max_i32_e32 v79, v21, v80
	v_min_i32_e32 v21, v21, v80
	v_max_i32_e32 v80, v44, v52
	v_min_i32_e32 v44, v44, v52
	v_max_i32_e32 v52, v40, v22
	v_min_i32_e32 v22, v40, v22
	v_max_i32_e32 v40, v54, v53
	v_min_i32_e32 v53, v54, v53
	v_max_i32_e32 v13, v15, v88
	v_min_i32_e32 v15, v15, v88
	v_max_i32_e32 v88, v2, v0
	v_min_i32_e32 v0, v2, v0
	v_max_i32_e32 v2, v4, v3
	v_min_i32_e32 v3, v4, v3
	v_max_i32_e32 v4, v6, v1
	v_min_i32_e32 v1, v6, v1
	v_max_i32_e32 v6, v5, v10
	v_min_i32_e32 v5, v5, v10
	v_max_i32_e32 v10, v7, v8
	v_min_i32_e32 v7, v7, v8
	v_max_i32_e32 v8, v12, v11
	v_min_i32_e32 v11, v12, v11
	v_max_i32_e32 v12, v14, v9
	v_min_i32_e32 v9, v14, v9
	v_max_i32_e32 v39, v38, v28
	v_min_i32_e32 v28, v38, v28
	v_max_i32_e32 v38, v27, v25
	v_min_i32_e32 v25, v27, v25
	v_max_i32_e32 v27, v42, v26
	v_min_i32_e32 v26, v42, v26
	v_max_i32_e32 v42, v24, v29
	v_min_i32_e32 v24, v24, v29
	v_max_i32_e32 v29, v36, v31
	v_min_i32_e32 v31, v36, v31
	v_max_i32_e32 v36, v33, v30
	v_min_i32_e32 v30, v33, v30
	v_max_i32_e32 v33, v34, v35
	v_min_i32_e32 v34, v34, v35
	v_max_i32_e32 v35, v37, v32
	v_min_i32_e32 v32, v37, v32
	v_max_i32_e32 v69, v68, v58
	v_min_i32_e32 v58, v68, v58
	v_max_i32_e32 v68, v57, v55
	v_min_i32_e32 v55, v57, v55
	v_max_i32_e32 v57, v70, v56
	v_min_i32_e32 v56, v70, v56
	v_max_i32_e32 v70, v51, v59
	v_min_i32_e32 v51, v51, v59
	v_max_i32_e32 v59, v66, v61
	v_min_i32_e32 v61, v66, v61
	v_max_i32_e32 v66, v63, v60
	v_min_i32_e32 v60, v63, v60
	v_max_i32_e32 v63, v64, v65
	v_min_i32_e32 v64, v64, v65
	v_max_i32_e32 v65, v67, v62
	v_min_i32_e32 v62, v67, v62
	v_max_i32_e32 v54, v41, v19
	v_min_i32_e32 v19, v41, v19
	v_max_i32_e32 v41, v23, v18
	v_min_i32_e32 v18, v23, v18
	v_max_i32_e32 v23, v78, v17
	v_min_i32_e32 v17, v78, v17
	v_max_i32_e32 v78, v16, v20
	v_min_i32_e32 v16, v16, v20
	v_max_i32_e32 v20, v22, v79
	v_min_i32_e32 v22, v22, v79
	v_max_i32_e32 v79, v52, v21
	v_min_i32_e32 v21, v52, v21
	v_max_i32_e32 v52, v53, v80
	v_min_i32_e32 v53, v53, v80
	v_max_i32_e32 v80, v40, v44
	v_min_i32_e32 v40, v40, v44
	v_max_i32_e32 v14, v13, v3
	v_min_i32_e32 v3, v13, v3
	v_max_i32_e32 v13, v15, v2
	v_min_i32_e32 v2, v15, v2
	v_max_i32_e32 v15, v88, v1
	v_min_i32_e32 v1, v88, v1
	v_max_i32_e32 v88, v0, v4
	v_min_i32_e32 v0, v0, v4
	v_max_i32_e32 v4, v11, v6
	v_min_i32_e32 v6, v11, v6
	v_max_i32_e32 v11, v8, v5
	v_min_i32_e32 v5, v8, v5
	v_max_i32_e32 v8, v9, v10
	v_min_i32_e32 v9, v9, v10
	v_max_i32_e32 v10, v12, v7
	v_min_i32_e32 v7, v12, v7
	v_max_i32_e32 v37, v39, v27
	v_min_i32_e32 v27, v39, v27
	v_max_i32_e32 v39, v38, v42
	v_min_i32_e32 v38, v38, v42
	v_max_i32_e32 v42, v28, v26
	v_min_i32_e32 v26, v28, v26
	v_max_i32_e32 v28, v25, v24
	v_min_i32_e32 v24, v25, v24
	v_max_i32_e32 v25, v34, v31
	v_min_i32_e32 v31, v34, v31
	v_max_i32_e32 v34, v32, v30
	v_min_i32_e32 v30, v32, v30
	v_max_i32_e32 v32, v33, v29
	v_min_i32_e32 v29, v33, v29
	v_max_i32_e32 v33, v35, v36
	v_min_i32_e32 v35, v35, v36
	v_max_i32_e32 v67, v69, v57
	v_min_i32_e32 v57, v69, v57
	v_max_i32_e32 v69, v68, v70
	v_min_i32_e32 v68, v68, v70
	v_max_i32_e32 v70, v58, v56
	v_min_i32_e32 v56, v58, v56
	v_max_i32_e32 v58, v55, v51
	v_min_i32_e32 v51, v55, v51
	v_max_i32_e32 v55, v64, v61
	v_min_i32_e32 v61, v64, v61
	v_max_i32_e32 v64, v62, v60
	v_min_i32_e32 v60, v62, v60
	v_max_i32_e32 v62, v63, v59
	v_min_i32_e32 v59, v63, v59
	v_max_i32_e32 v63, v65, v66
	v_min_i32_e32 v65, v65, v66
	v_max_i32_e32 v44, v54, v23
	v_min_i32_e32 v23, v54, v23
	v_max_i32_e32 v54, v41, v78
	v_min_i32_e32 v41, v41, v78
	v_max_i32_e32 v78, v19, v17
	v_min_i32_e32 v17, v19, v17
	v_max_i32_e32 v19, v18, v16
	v_min_i32_e32 v16, v18, v16
	v_max_i32_e32 v18, v53, v22
	v_min_i32_e32 v22, v53, v22
	v_max_i32_e32 v53, v40, v21
	v_min_i32_e32 v21, v40, v21
	v_max_i32_e32 v40, v52, v20
	v_min_i32_e32 v20, v52, v20
	v_max_i32_e32 v52, v80, v79
	v_min_i32_e32 v79, v80, v79
	v_max_i32_e32 v12, v14, v15
	v_min_i32_e32 v14, v14, v15
	v_max_i32_e32 v15, v13, v88
	v_min_i32_e32 v13, v13, v88
	v_max_i32_e32 v88, v3, v1
	v_min_i32_e32 v1, v3, v1
	v_max_i32_e32 v3, v2, v0
	v_min_i32_e32 v0, v2, v0
	v_max_i32_e32 v2, v9, v6
	v_min_i32_e32 v6, v9, v6
	v_max_i32_e32 v9, v7, v5
	v_min_i32_e32 v5, v7, v5
	v_max_i32_e32 v7, v8, v4
	v_min_i32_e32 v4, v8, v4
	v_max_i32_e32 v8, v10, v11
	v_min_i32_e32 v10, v10, v11
	v_max_i32_e32 v36, v37, v39
	v_min_i32_e32 v37, v37, v39
	v_max_i32_e32 v39, v27, v38
	v_min_i32_e32 v27, v27, v38
	v_max_i32_e32 v38, v42, v28
	v_min_i32_e32 v28, v42, v28
	v_max_i32_e32 v42, v26, v24
	v_min_i32_e32 v24, v26, v24
	v_max_i32_e32 v26, v30, v31
	v_min_i32_e32 v30, v30, v31
	v_max_i32_e32 v31, v34, v25
	v_min_i32_e32 v25, v34, v25
	v_max_i32_e32 v34, v35, v29
	v_min_i32_e32 v29, v35, v29
	v_max_i32_e32 v35, v33, v32
	v_min_i32_e32 v32, v33, v32
	v_max_i32_e32 v66, v67, v69
	v_min_i32_e32 v67, v67, v69
	v_max_i32_e32 v69, v57, v68
	v_min_i32_e32 v57, v57, v68
	v_max_i32_e32 v68, v70, v58
	v_min_i32_e32 v58, v70, v58
	v_max_i32_e32 v70, v56, v51
	v_min_i32_e32 v51, v56, v51
	v_max_i32_e32 v56, v60, v61
	v_min_i32_e32 v60, v60, v61
	v_max_i32_e32 v61, v64, v55
	v_min_i32_e32 v55, v64, v55
	v_max_i32_e32 v64, v65, v59
	v_min_i32_e32 v59, v65, v59
	v_max_i32_e32 v65, v63, v62
	v_min_i32_e32 v62, v63, v62
	v_max_i32_e32 v80, v44, v54
	v_min_i32_e32 v44, v44, v54
	v_max_i32_e32 v54, v23, v41
	v_min_i32_e32 v23, v23, v41
	v_max_i32_e32 v41, v78, v19
	v_min_i32_e32 v19, v78, v19
	v_max_i32_e32 v78, v17, v16
	v_min_i32_e32 v16, v17, v16
	v_max_i32_e32 v17, v21, v22
	v_min_i32_e32 v21, v21, v22
	v_max_i32_e32 v22, v53, v18
	v_min_i32_e32 v18, v53, v18
	v_max_i32_e32 v53, v79, v20
	v_min_i32_e32 v20, v79, v20
	v_max_i32_e32 v79, v52, v40
	v_min_i32_e32 v40, v52, v40
	v_max_i32_e32 v11, v12, v15
	v_min_i32_e32 v12, v12, v15
	v_max_i32_e32 v15, v14, v13
	v_min_i32_e32 v13, v14, v13
	v_max_i32_e32 v14, v88, v3
	v_min_i32_e32 v3, v88, v3
	v_max_i32_e32 v88, v1, v0
	v_min_i32_e32 v0, v1, v0
	v_max_i32_e32 v1, v5, v6
	v_min_i32_e32 v5, v5, v6
	v_max_i32_e32 v6, v9, v2
	v_min_i32_e32 v2, v9, v2
	v_max_i32_e32 v9, v10, v4
	v_min_i32_e32 v4, v10, v4
	v_max_i32_e32 v10, v8, v7
	v_min_i32_e32 v7, v8, v7
	v_max_i32_e32 v33, v36, v30
	v_min_i32_e32 v30, v36, v30
	v_max_i32_e32 v36, v37, v26
	v_min_i32_e32 v26, v37, v26
	v_max_i32_e32 v37, v39, v25
	v_min_i32_e32 v25, v39, v25
	v_max_i32_e32 v39, v27, v31
	v_min_i32_e32 v27, v27, v31
	v_max_i32_e32 v31, v38, v29
	v_min_i32_e32 v29, v38, v29
	v_max_i32_e32 v38, v28, v34
	v_min_i32_e32 v28, v28, v34
	v_max_i32_e32 v34, v42, v32
	v_min_i32_e32 v32, v42, v32
	v_max_i32_e32 v42, v24, v35
	v_min_i32_e32 v24, v24, v35
	v_max_i32_e32 v63, v66, v60
	v_min_i32_e32 v60, v66, v60
	v_max_i32_e32 v66, v67, v56
	v_min_i32_e32 v56, v67, v56
	v_max_i32_e32 v67, v69, v55
	v_min_i32_e32 v55, v69, v55
	v_max_i32_e32 v69, v57, v61
	v_min_i32_e32 v57, v57, v61
	v_max_i32_e32 v61, v68, v59
	v_min_i32_e32 v59, v68, v59
	v_max_i32_e32 v68, v58, v64
	v_min_i32_e32 v58, v58, v64
	v_max_i32_e32 v64, v70, v62
	v_min_i32_e32 v62, v70, v62
	v_max_i32_e32 v70, v51, v65
	v_min_i32_e32 v51, v51, v65
	v_max_i32_e32 v52, v80, v21
	v_min_i32_e32 v21, v80, v21
	v_max_i32_e32 v80, v44, v17
	v_min_i32_e32 v17, v44, v17
	v_max_i32_e32 v44, v54, v18
	v_min_i32_e32 v18, v54, v18
	v_max_i32_e32 v54, v23, v22
	v_min_i32_e32 v22, v23, v22
	v_max_i32_e32 v23, v41, v20
	v_min_i32_e32 v20, v41, v20
	v_max_i32_e32 v41, v19, v53
	v_min_i32_e32 v19, v19, v53
	v_max_i32_e32 v53, v78, v40
	v_min_i32_e32 v40, v78, v40
	v_max_i32_e32 v78, v16, v79
	v_min_i32_e32 v16, v16, v79
	v_max_i32_e32 v8, v11, v5
	v_min_i32_e32 v5, v11, v5
	v_max_i32_e32 v11, v12, v1
	v_min_i32_e32 v1, v12, v1
	v_max_i32_e32 v12, v15, v2
	v_min_i32_e32 v2, v15, v2
	v_max_i32_e32 v15, v13, v6
	v_min_i32_e32 v6, v13, v6
	v_max_i32_e32 v13, v14, v4
	v_min_i32_e32 v4, v14, v4
	v_max_i32_e32 v14, v3, v9
	v_min_i32_e32 v3, v3, v9
	v_max_i32_e32 v9, v88, v7
	v_min_i32_e32 v7, v88, v7
	v_max_i32_e32 v88, v0, v10
	v_min_i32_e32 v0, v0, v10
	v_max_i32_e32 v35, v33, v31
	v_min_i32_e32 v31, v33, v31
	v_max_i32_e32 v33, v36, v38
	v_min_i32_e32 v36, v36, v38
	v_max_i32_e32 v38, v37, v34
	v_min_i32_e32 v34, v37, v34
	v_max_i32_e32 v37, v39, v42
	v_min_i32_e32 v39, v39, v42
	v_max_i32_e32 v42, v30, v29
	v_min_i32_e32 v29, v30, v29
	v_max_i32_e32 v30, v26, v28
	v_min_i32_e32 v26, v26, v28
	v_max_i32_e32 v28, v25, v32
	v_min_i32_e32 v25, v25, v32
	v_max_i32_e32 v32, v27, v24
	v_min_i32_e32 v24, v27, v24
	v_max_i32_e32 v65, v63, v61
	v_min_i32_e32 v61, v63, v61
	v_max_i32_e32 v63, v66, v68
	v_min_i32_e32 v66, v66, v68
	v_max_i32_e32 v68, v67, v64
	v_min_i32_e32 v64, v67, v64
	v_max_i32_e32 v67, v69, v70
	v_min_i32_e32 v69, v69, v70
	v_max_i32_e32 v70, v60, v59
	v_min_i32_e32 v59, v60, v59
	v_max_i32_e32 v60, v56, v58
	v_min_i32_e32 v56, v56, v58
	v_max_i32_e32 v58, v55, v62
	v_min_i32_e32 v55, v55, v62
	v_max_i32_e32 v62, v57, v51
	v_min_i32_e32 v51, v57, v51
	v_max_i32_e32 v79, v52, v23
	v_min_i32_e32 v23, v52, v23
	v_max_i32_e32 v52, v80, v41
	v_min_i32_e32 v41, v80, v41
	v_max_i32_e32 v80, v44, v53
	v_min_i32_e32 v44, v44, v53
	v_max_i32_e32 v53, v54, v78
	v_min_i32_e32 v54, v54, v78
	v_max_i32_e32 v78, v21, v20
	v_min_i32_e32 v20, v21, v20
	v_max_i32_e32 v21, v17, v19
	v_min_i32_e32 v17, v17, v19
	v_max_i32_e32 v19, v18, v40
	v_min_i32_e32 v18, v18, v40
	v_max_i32_e32 v40, v22, v16
	v_min_i32_e32 v16, v22, v16
	v_max_i32_e32 v10, v8, v13
	v_min_i32_e32 v8, v8, v13
	v_max_i32_e32 v13, v11, v14
	v_min_i32_e32 v11, v11, v14
	v_max_i32_e32 v14, v12, v9
	v_min_i32_e32 v9, v12, v9
	v_max_i32_e32 v12, v15, v88
	v_min_i32_e32 v15, v15, v88
	v_max_i32_e32 v88, v5, v4
	v_min_i32_e32 v4, v5, v4
	v_max_i32_e32 v5, v1, v3
	v_min_i32_e32 v1, v1, v3
	v_max_i32_e32 v3, v2, v7
	v_min_i32_e32 v2, v2, v7
	v_max_i32_e32 v7, v6, v0
	v_min_i32_e32 v0, v6, v0
	v_max_i32_e32 v27, v35, v38
	v_min_i32_e32 v35, v35, v38
	v_max_i32_e32 v38, v33, v37
	v_min_i32_e32 v33, v33, v37
	v_max_i32_e32 v37, v31, v34
	v_min_i32_e32 v31, v31, v34
	v_max_i32_e32 v34, v36, v39
	v_min_i32_e32 v36, v36, v39
	v_max_i32_e32 v39, v42, v28
	v_min_i32_e32 v28, v42, v28
	v_max_i32_e32 v42, v30, v32
	v_min_i32_e32 v30, v30, v32
	v_max_i32_e32 v32, v29, v25
	v_min_i32_e32 v25, v29, v25
	v_max_i32_e32 v29, v26, v24
	v_min_i32_e32 v24, v26, v24
	v_max_i32_e32 v57, v65, v68
	v_min_i32_e32 v65, v65, v68
	v_max_i32_e32 v68, v63, v67
	v_min_i32_e32 v63, v63, v67
	v_max_i32_e32 v67, v61, v64
	v_min_i32_e32 v61, v61, v64
	v_max_i32_e32 v64, v66, v69
	v_min_i32_e32 v66, v66, v69
	v_max_i32_e32 v69, v70, v58
	v_min_i32_e32 v58, v70, v58
	v_max_i32_e32 v70, v60, v62
	v_min_i32_e32 v60, v60, v62
	v_max_i32_e32 v62, v59, v55
	v_min_i32_e32 v55, v59, v55
	v_max_i32_e32 v59, v56, v51
	v_min_i32_e32 v51, v56, v51
	v_max_i32_e32 v22, v79, v80
	v_min_i32_e32 v79, v79, v80
	v_max_i32_e32 v80, v52, v53
	v_min_i32_e32 v52, v52, v53
	v_max_i32_e32 v53, v23, v44
	v_min_i32_e32 v23, v23, v44
	v_max_i32_e32 v44, v41, v54
	v_min_i32_e32 v41, v41, v54
	v_max_i32_e32 v54, v78, v19
	v_min_i32_e32 v19, v78, v19
	v_max_i32_e32 v78, v21, v40
	v_min_i32_e32 v21, v21, v40
	v_max_i32_e32 v40, v20, v18
	v_min_i32_e32 v18, v20, v18
	v_max_i32_e32 v20, v17, v16
	v_min_i32_e32 v16, v17, v16
	v_max_i32_e32 v6, v10, v14
	v_min_i32_e32 v10, v10, v14
	v_max_i32_e32 v14, v13, v12
	v_min_i32_e32 v12, v13, v12
	v_max_i32_e32 v13, v8, v9
	v_min_i32_e32 v8, v8, v9
	v_max_i32_e32 v9, v11, v15
	v_min_i32_e32 v11, v11, v15
	v_max_i32_e32 v15, v88, v3
	v_min_i32_e32 v3, v88, v3
	v_max_i32_e32 v88, v5, v7
	v_min_i32_e32 v5, v5, v7
	v_max_i32_e32 v7, v4, v2
	v_min_i32_e32 v2, v4, v2
	v_max_i32_e32 v4, v1, v0
	v_min_i32_e32 v0, v1, v0
	v_min_i32_e32 v26, v27, v38
	v_min_i32_e32 v43, v35, v33
	v_min_i32_e32 v45, v37, v34
	v_min_i32_e32 v46, v31, v36
	v_min_i32_e32 v47, v39, v42
	v_min_i32_e32 v48, v28, v30
	v_min_i32_e32 v49, v32, v29
	v_min_i32_e32 v50, v25, v24
	v_min_i32_e32 v56, v57, v68
	v_min_i32_e32 v71, v65, v63
	v_min_i32_e32 v72, v67, v64
	v_min_i32_e32 v73, v61, v66
	v_min_i32_e32 v74, v69, v70
	v_min_i32_e32 v75, v58, v60
	v_min_i32_e32 v76, v62, v59
	v_min_i32_e32 v77, v55, v51
	v_min_i32_e32 v17, v22, v80
	v_min_i32_e32 v81, v79, v52
	v_min_i32_e32 v82, v53, v44
	v_min_i32_e32 v83, v23, v41
	v_min_i32_e32 v84, v54, v78
	v_min_i32_e32 v85, v19, v21
	v_min_i32_e32 v86, v40, v20
	v_min_i32_e32 v87, v18, v16
	v_min_i32_e32 v1, v6, v14
	v_min_i32_e32 v89, v10, v12
	v_min_i32_e32 v90, v13, v9
	v_min_i32_e32 v91, v8, v11
	v_min_i32_e32 v92, v15, v88
	v_min_i32_e32 v93, v3, v5
	v_min_i32_e32 v94, v7, v4
	v_min_i32_e32 v95, v2, v0
	v_max3_i32 v27, v27, v38, v77
	v_max3_i32 v26, v26, v55, v51
	v_max3_i32 v33, v35, v33, v76
	v_max3_i32 v35, v43, v62, v59
	v_max3_i32 v34, v37, v34, v75
	v_max3_i32 v37, v45, v58, v60
	v_max3_i32 v31, v31, v36, v74
	v_max3_i32 v36, v46, v69, v70
	v_max3_i32 v38, v39, v42, v73
	v_max3_i32 v39, v47, v61, v66
	v_max3_i32 v28, v28, v30, v72
	v_max3_i32 v30, v48, v67, v64
	v_max3_i32 v29, v32, v29, v71
	v_max3_i32 v32, v49, v65, v63
	v_max3_i32 v24, v25, v24, v56
	v_max3_i32 v25, v50, v57, v68
	v_max3_i32 v22, v22, v80, v95
	v_max3_i32 v0, v17, v2, v0
	v_max3_i32 v2, v79, v52, v94
	v_max3_i32 v4, v81, v7, v4
	v_max3_i32 v7, v53, v44, v93
	v_max3_i32 v3, v82, v3, v5
	v_max3_i32 v5, v23, v41, v92
	v_max3_i32 v15, v83, v15, v88
	v_max3_i32 v17, v54, v78, v91
	v_max3_i32 v8, v84, v8, v11
	v_max3_i32 v11, v19, v21, v90
	v_max3_i32 v9, v85, v13, v9
	v_max3_i32 v13, v40, v20, v89
	v_max3_i32 v10, v86, v10, v12
	v_max3_i32 v1, v18, v16, v1
	v_max3_i32 v6, v87, v6, v14
	v_max_i32_e32 v42, v27, v38
	v_min_i32_e32 v27, v27, v38
	v_max_i32_e32 v38, v26, v39
	v_min_i32_e32 v26, v26, v39
	v_max_i32_e32 v39, v33, v28
	v_min_i32_e32 v28, v33, v28
	v_max_i32_e32 v33, v35, v30
	v_min_i32_e32 v30, v35, v30
	v_max_i32_e32 v35, v34, v29
	v_min_i32_e32 v29, v34, v29
	v_max_i32_e32 v34, v37, v32
	v_min_i32_e32 v32, v37, v32
	v_max_i32_e32 v37, v31, v24
	v_min_i32_e32 v24, v31, v24
	v_max_i32_e32 v31, v36, v25
	v_min_i32_e32 v25, v36, v25
	v_max_i32_e32 v12, v22, v17
	v_min_i32_e32 v14, v22, v17
	v_max_i32_e32 v16, v0, v8
	v_min_i32_e32 v0, v0, v8
	v_max_i32_e32 v8, v2, v11
	v_min_i32_e32 v2, v2, v11
	v_max_i32_e32 v11, v4, v9
	v_min_i32_e32 v4, v4, v9
	v_max_i32_e32 v9, v7, v13
	v_min_i32_e32 v7, v7, v13
	v_max_i32_e32 v13, v3, v10
	v_min_i32_e32 v3, v3, v10
	v_max_i32_e32 v10, v5, v1
	v_min_i32_e32 v1, v5, v1
	v_max_i32_e32 v5, v15, v6
	v_min_i32_e32 v6, v15, v6
	v_max_i32_e32 v36, v42, v35
	v_min_i32_e32 v35, v42, v35
	v_max_i32_e32 v42, v38, v34
	v_min_i32_e32 v34, v38, v34
	v_max_i32_e32 v38, v39, v37
	v_min_i32_e32 v37, v39, v37
	v_max_i32_e32 v39, v33, v31
	v_min_i32_e32 v31, v33, v31
	v_max_i32_e32 v33, v27, v29
	v_min_i32_e32 v27, v27, v29
	v_max_i32_e32 v29, v26, v32
	v_min_i32_e32 v26, v26, v32
	v_max_i32_e32 v32, v28, v24
	v_min_i32_e32 v24, v28, v24
	v_max_i32_e32 v28, v30, v25
	v_min_i32_e32 v25, v30, v25
	v_max_i32_e32 v15, v12, v9
	v_min_i32_e32 v9, v12, v9
	v_max_i32_e32 v12, v16, v13
	v_min_i32_e32 v13, v16, v13
	v_max_i32_e32 v16, v8, v10
	v_min_i32_e32 v8, v8, v10
	v_max_i32_e32 v10, v11, v5
	v_min_i32_e32 v5, v11, v5
	v_max_i32_e32 v11, v14, v7
	v_min_i32_e32 v7, v14, v7
	v_max_i32_e32 v14, v0, v3
	v_min_i32_e32 v0, v0, v3
	v_max_i32_e32 v3, v2, v1
	v_min_i32_e32 v1, v2, v1
	v_max_i32_e32 v2, v4, v6
	v_min_i32_e32 v4, v4, v6
	v_max_i32_e32 v30, v36, v38
	v_min_i32_e32 v36, v36, v38
	v_max_i32_e32 v38, v42, v39
	v_min_i32_e32 v39, v42, v39
	v_max_i32_e32 v42, v35, v37
	v_min_i32_e32 v35, v35, v37
	v_max_i32_e32 v37, v34, v31
	v_min_i32_e32 v31, v34, v31
	v_max_i32_e32 v34, v33, v32
	v_min_i32_e32 v32, v33, v32
	v_max_i32_e32 v33, v29, v28
	v_min_i32_e32 v28, v29, v28
	v_max_i32_e32 v29, v27, v24
	v_min_i32_e32 v24, v27, v24
	v_max_i32_e32 v27, v26, v25
	v_min_i32_e32 v25, v26, v25
	v_max_i32_e32 v6, v15, v16
	v_min_i32_e32 v15, v15, v16
	v_max_i32_e32 v16, v12, v10
	v_min_i32_e32 v10, v12, v10
	v_max_i32_e32 v12, v9, v8
	v_min_i32_e32 v8, v9, v8
	v_max_i32_e32 v9, v13, v5
	v_min_i32_e32 v5, v13, v5
	v_max_i32_e32 v13, v11, v3
	v_min_i32_e32 v3, v11, v3
	v_max_i32_e32 v11, v14, v2
	v_min_i32_e32 v2, v14, v2
	v_max_i32_e32 v14, v7, v1
	v_min_i32_e32 v1, v7, v1
	v_max_i32_e32 v7, v0, v4
	v_min_i32_e32 v0, v0, v4
	v_min_i32_e32 v26, v30, v38
	v_min_i32_e32 v43, v36, v39
	v_min_i32_e32 v45, v42, v37
	v_min_i32_e32 v46, v35, v31
	v_min_i32_e32 v47, v34, v33
	v_min_i32_e32 v48, v32, v28
	v_min_i32_e32 v49, v29, v27
	v_min_i32_e32 v50, v24, v25
	v_min_i32_e32 v4, v6, v16
	v_min_i32_e32 v17, v15, v10
	v_min_i32_e32 v18, v12, v9
	v_min_i32_e32 v19, v8, v5
	v_min_i32_e32 v20, v13, v11
	v_min_i32_e32 v21, v3, v2
	v_min_i32_e32 v22, v14, v7
	v_min_i32_e32 v23, v1, v0
	v_max3_i32 v23, v30, v38, v23
	v_max3_i32 v0, v26, v1, v0
	v_max3_i32 v1, v36, v39, v22
	v_max3_i32 v7, v43, v14, v7
	v_max3_i32 v14, v42, v37, v21
	v_max3_i32 v2, v45, v3, v2
	v_max3_i32 v3, v35, v31, v20
	v_max3_i32 v11, v46, v13, v11
	v_max3_i32 v13, v34, v33, v19
	v_max3_i32 v5, v47, v8, v5
	v_max3_i32 v8, v32, v28, v18
	v_max3_i32 v9, v48, v12, v9
	v_max3_i32 v12, v29, v27, v17
	v_max3_i32 v10, v49, v15, v10
	v_max3_i32 v4, v24, v25, v4
	v_max3_i32 v6, v50, v6, v16
	v_max_i32_e32 v15, v23, v13
	v_min_i32_e32 v13, v23, v13
	v_max_i32_e32 v16, v0, v5
	v_min_i32_e32 v0, v0, v5
	v_max_i32_e32 v5, v1, v8
	v_min_i32_e32 v1, v1, v8
	v_max_i32_e32 v8, v7, v9
	v_min_i32_e32 v7, v7, v9
	v_max_i32_e32 v9, v14, v12
	v_min_i32_e32 v12, v14, v12
	v_max_i32_e32 v14, v2, v10
	v_min_i32_e32 v2, v2, v10
	v_max_i32_e32 v10, v3, v4
	v_min_i32_e32 v3, v3, v4
	v_max_i32_e32 v4, v11, v6
	v_min_i32_e32 v6, v11, v6
	v_max_i32_e32 v11, v15, v9
	v_min_i32_e32 v9, v15, v9
	v_max_i32_e32 v15, v16, v14
	v_min_i32_e32 v14, v16, v14
	v_max_i32_e32 v16, v5, v10
	v_min_i32_e32 v5, v5, v10
	v_max_i32_e32 v10, v8, v4
	v_min_i32_e32 v4, v8, v4
	v_max_i32_e32 v8, v13, v12
	v_min_i32_e32 v12, v13, v12
	v_max_i32_e32 v13, v0, v2
	v_min_i32_e32 v0, v0, v2
	v_max_i32_e32 v2, v1, v3
	v_min_i32_e32 v1, v1, v3
	v_max_i32_e32 v3, v7, v6
	v_min_i32_e32 v6, v7, v6
	v_max_i32_e32 v7, v11, v16
	v_min_i32_e32 v11, v11, v16
	v_max_i32_e32 v16, v15, v10
	v_min_i32_e32 v10, v15, v10
	v_max_i32_e32 v15, v9, v5
	v_min_i32_e32 v5, v9, v5
	v_max_i32_e32 v9, v14, v4
	v_min_i32_e32 v4, v14, v4
	v_max_i32_e32 v14, v8, v2
	v_min_i32_e32 v2, v8, v2
	v_max_i32_e32 v8, v13, v3
	v_min_i32_e32 v3, v13, v3
	v_max_i32_e32 v13, v12, v1
	v_min_i32_e32 v1, v12, v1
	v_max_i32_e32 v12, v0, v6
	v_min_i32_e32 v0, v0, v6
	v_max_i32_e32 v6, v7, v16
	v_min_i32_e32 v7, v7, v16
	v_max_i32_e32 v16, v11, v10
	v_min_i32_e32 v10, v11, v10
	v_max_i32_e32 v11, v15, v9
	v_min_i32_e32 v9, v15, v9
	v_max_i32_e32 v15, v5, v4
	v_min_i32_e32 v4, v5, v4
	v_max_i32_e32 v5, v14, v8
	v_min_i32_e32 v8, v14, v8
	v_max_i32_e32 v14, v2, v3
	v_min_i32_e32 v2, v2, v3
	v_max_i32_e32 v3, v13, v12
	v_min_i32_e32 v13, v13, v12
	v_and_b32_e32 v12, 64, v188
	v_max_i32_e32 v17, v1, v0
	v_min_i32_e32 v0, v1, v0
	v_xor_b32_e32 v1, 32, v188
	v_add_u32_e32 v12, 64, v12
	v_cmp_lt_i32_e32 vcc, v1, v12
	s_barrier
	s_nop 0
	v_cndmask_b32_e32 v1, v188, v1, vcc
	v_lshlrev_b32_e32 v12, 2, v1
	ds_bpermute_b32 v1, v12, v6
	ds_bpermute_b32 v18, v12, v7
	ds_bpermute_b32 v19, v12, v16
	ds_bpermute_b32 v20, v12, v10
	ds_bpermute_b32 v21, v12, v11
	ds_bpermute_b32 v22, v12, v9
	ds_bpermute_b32 v23, v12, v15
	ds_bpermute_b32 v24, v12, v4
	ds_bpermute_b32 v25, v12, v5
	ds_bpermute_b32 v26, v12, v8
	ds_bpermute_b32 v27, v12, v14
	ds_bpermute_b32 v28, v12, v0
	ds_bpermute_b32 v29, v12, v17
	ds_bpermute_b32 v30, v12, v13
	ds_bpermute_b32 v31, v12, v3
	ds_bpermute_b32 v32, v12, v2
	s_waitcnt lgkmcnt(4)
	v_max_i32_e32 v6, v6, v28
	s_waitcnt lgkmcnt(3)
	v_max_i32_e32 v7, v7, v29
	s_waitcnt lgkmcnt(2)
	v_max_i32_e32 v16, v16, v30
	s_waitcnt lgkmcnt(1)
	v_max_i32_e32 v10, v10, v31
	s_waitcnt lgkmcnt(0)
	v_max_i32_e32 v11, v11, v32
	v_max_i32_e32 v9, v9, v27
	v_max_i32_e32 v15, v15, v26
	v_max_i32_e32 v4, v4, v25
	v_max_i32_e32 v5, v5, v24
	v_max_i32_e32 v8, v8, v23
	v_max_i32_e32 v14, v14, v22
	v_max_i32_e32 v2, v2, v21
	v_max_i32_e32 v3, v3, v20
	v_max_i32_e32 v13, v13, v19
	v_max_i32_e32 v17, v17, v18
	v_max_i32_e32 v0, v0, v1
	v_max_i32_e32 v1, v6, v5
	v_min_i32_e32 v5, v6, v5
	v_max_i32_e32 v6, v7, v8
	v_min_i32_e32 v7, v7, v8
	v_max_i32_e32 v8, v16, v14
	v_min_i32_e32 v14, v16, v14
	v_max_i32_e32 v16, v10, v2
	v_min_i32_e32 v2, v10, v2
	v_max_i32_e32 v10, v11, v3
	v_min_i32_e32 v3, v11, v3
	v_max_i32_e32 v11, v9, v13
	v_min_i32_e32 v9, v9, v13
	v_max_i32_e32 v13, v15, v17
	v_min_i32_e32 v15, v15, v17
	v_max_i32_e32 v17, v4, v0
	v_min_i32_e32 v0, v4, v0
	v_max_i32_e32 v4, v1, v10
	v_min_i32_e32 v1, v1, v10
	v_max_i32_e32 v10, v6, v11
	v_min_i32_e32 v6, v6, v11
	v_max_i32_e32 v11, v8, v13
	v_min_i32_e32 v8, v8, v13
	v_max_i32_e32 v13, v16, v17
	v_min_i32_e32 v16, v16, v17
	v_max_i32_e32 v17, v5, v3
	v_min_i32_e32 v3, v5, v3
	v_max_i32_e32 v5, v7, v9
	v_min_i32_e32 v7, v7, v9
	v_max_i32_e32 v9, v14, v15
	v_min_i32_e32 v14, v14, v15
	v_max_i32_e32 v15, v2, v0
	v_min_i32_e32 v0, v2, v0
	v_max_i32_e32 v2, v4, v11
	v_min_i32_e32 v4, v4, v11
	v_max_i32_e32 v11, v10, v13
	v_min_i32_e32 v10, v10, v13
	v_max_i32_e32 v13, v1, v8
	v_min_i32_e32 v1, v1, v8
	v_max_i32_e32 v8, v6, v16
	v_min_i32_e32 v6, v6, v16
	v_max_i32_e32 v16, v17, v9
	v_min_i32_e32 v9, v17, v9
	v_max_i32_e32 v17, v5, v15
	v_min_i32_e32 v5, v5, v15
	v_max_i32_e32 v15, v3, v14
	v_min_i32_e32 v3, v3, v14
	v_max_i32_e32 v14, v7, v0
	v_min_i32_e32 v0, v7, v0
	v_max_i32_e32 v7, v2, v11
	v_min_i32_e32 v2, v2, v11
	v_max_i32_e32 v25, v3, v0
	v_min_i32_e32 v26, v3, v0
	v_ashrrev_i32_e32 v0, 31, v7
	v_max_i32_e32 v11, v4, v10
	v_bitop3_b32 v20, v0, v7, s11 bitop3:0x6c
	v_ashrrev_i32_e32 v0, 31, v2
	v_min_i32_e32 v4, v4, v10
	v_bitop3_b32 v19, v0, v2, s11 bitop3:0x6c
	v_ashrrev_i32_e32 v0, 31, v11
	v_max_i32_e32 v10, v13, v8
	v_bitop3_b32 v18, v0, v11, s11 bitop3:0x6c
	v_ashrrev_i32_e32 v0, 31, v4
	v_min_i32_e32 v8, v13, v8
	v_max_i32_e32 v13, v1, v6
	v_min_i32_e32 v1, v1, v6
	v_max_i32_e32 v6, v16, v17
	v_min_i32_e32 v21, v16, v17
	v_bitop3_b32 v17, v0, v4, s11 bitop3:0x6c
	v_ashrrev_i32_e32 v0, 31, v10
	v_bitop3_b32 v16, v0, v10, s11 bitop3:0x6c
	v_ashrrev_i32_e32 v0, 31, v8
	v_max_i32_e32 v23, v15, v14
	v_min_i32_e32 v24, v15, v14
	v_bitop3_b32 v15, v0, v8, s11 bitop3:0x6c
	v_ashrrev_i32_e32 v0, 31, v13
	v_bitop3_b32 v14, v0, v13, s11 bitop3:0x6c
	v_ashrrev_i32_e32 v0, 31, v1
	v_bitop3_b32 v13, v0, v1, s11 bitop3:0x6c
	v_ashrrev_i32_e32 v0, 31, v6
	v_ashrrev_i32_e32 v1, 31, v21
	v_max_i32_e32 v22, v9, v5
	v_min_i32_e32 v9, v9, v5
	v_and_b32_e32 v0, 0x7fffffff, v0
	v_and_b32_e32 v2, 0x7fffffff, v1
	v_xor_b32_e32 v1, v0, v6
	v_xor_b32_e32 v0, v2, v21
	v_ashrrev_i32_e32 v2, 31, v22
	v_ashrrev_i32_e32 v3, 31, v9
	v_and_b32_e32 v2, 0x7fffffff, v2
	v_and_b32_e32 v3, 0x7fffffff, v3
	v_xor_b32_e32 v5, v2, v22
	v_xor_b32_e32 v4, v3, v9
	v_ashrrev_i32_e32 v2, 31, v23
	v_ashrrev_i32_e32 v3, 31, v24
	v_and_b32_e32 v2, 0x7fffffff, v2
	v_and_b32_e32 v6, 0x7fffffff, v3
	v_xor_b32_e32 v3, v2, v23
	v_xor_b32_e32 v2, v6, v24
	v_ashrrev_i32_e32 v6, 31, v25
	v_bitop3_b32 v11, v6, v25, s11 bitop3:0x6c
	v_ashrrev_i32_e32 v6, 31, v26
	v_bitop3_b32 v10, v6, v26, s11 bitop3:0x6c
	s_and_b64 vcc, exec, s[56:57]
	s_cbranch_vccnz .LBB0_1001
	v_mov_b32_e32 v221, v20
	v_mov_b32_e32 v222, v19
	v_mov_b32_e32 v223, v18
	v_mov_b32_e32 v224, v17
	v_mov_b32_e32 v225, v16
	v_mov_b32_e32 v226, v15
	v_mov_b32_e32 v227, v14
	v_mov_b32_e32 v228, v13
	v_mov_b32_e32 v229, v11
	v_mov_b32_e32 v230, v10
	v_mov_b64_e32 v[154:155], v[2:3]
	v_mov_b64_e32 v[156:157], v[4:5]
	v_mov_b64_e32 v[158:159], v[0:1]
	s_branch .LBB0_1003
